# RG-LRU carry phase: 256-step chain fully unrolled with its (P,Hend) loads issued 20 steps ahead (counted vmcnt) instead of load-8/wait/compute
# speedup vs baseline: 1.0048x; 1.0040x over previous
.LBB0_1155:
	s_or_b64 exec, exec, s[6:7]
	s_waitcnt lgkmcnt(0)
	v_mov_b32_e32 v0, v224
	s_barrier
	v_readlane_b32 s18, v255, 19
	v_readfirstlane_b32 s6, v0
	s_cmp_lt_u32 s6, 64
	s_cselect_b64 s[6:7], -1, 0
	v_readlane_b32 s19, v255, 20
	s_and_b64 s[6:7], s[18:19], s[6:7]
	s_and_b64 vcc, exec, s[6:7]
	s_cbranch_vccz .LBB0_1158
	s_mov_b64 s[6:7], s[0:1]
	v_readlane_b32 s3, v255, 21
	s_mov_b64 s[18:19], s[0:1]
	s_load_dwordx2 s[6:7], s[6:7], 0xe8
	v_and_or_b32 v0, v0, 63, s3
	s_mov_b64 s[22:23], s[0:1]
	v_mul_hi_i32 v1, v0, s81
	s_load_dwordx2 s[18:19], s[18:19], 0xe8
	v_lshrrev_b32_e32 v2, 31, v1
	v_ashrrev_i32_e32 v1, 7, v1
	s_load_dwordx2 s[22:23], s[22:23], 0xe8
	v_add_u32_e32 v1, v1, v2
	v_mul_i32_i24_e32 v2, 0x300, v1
	v_sub_u32_e32 v0, v0, v2
	s_waitcnt lgkmcnt(0)
	s_add_u32 s6, s6, 0x300000
	v_and_b32_e32 v2, 1, v1
	s_addc_u32 s7, s7, 0
	s_waitcnt vmcnt(1)
	v_lshlrev_b32_e32 v4, 8, v1
	v_ashrrev_i32_e32 v1, 31, v0
	s_add_u32 s18, s18, 0x600000
	v_cmp_eq_u32_e32 vcc, 0, v2
	v_lshl_add_u64 v[2:3], v[0:1], 2, s[22:23]
	s_mov_b64 s[22:23], 0x900000
	s_mov_b32 s20, 7
	s_addc_u32 s19, s19, 0
	v_lshl_add_u64 v[2:3], v[2:3], 0, s[22:23]
	s_waitcnt vmcnt(0)
	v_mov_b32_e32 v5, 0
	s_movk_i32 s21, 0xf8
	v_mov_b32_e32 v16, 0xff
	v_mov_b32_e32 v17, 0
	v_cndmask_b32_e32 v16, v16, v17, vcc
	v_add_u32_e32 v16, v16, v4
	v_mad_i64_i32 v[6:7], s[22:23], v16, s54, v[0:1]
	v_lshlrev_b64 v[6:7], 2, v[6:7]
	v_lshl_add_u64 v[8:9], s[18:19], 0, v[6:7]
	v_lshl_add_u64 v[6:7], s[6:7], 0, v[6:7]
	v_mad_i64_i32 v[10:11], s[22:23], v16, s69, v[2:3]
	s_lshl_b32 s22, s54, 2
	v_mov_b32_e32 v12, s22
	v_sub_u32_e32 v18, 0, v12
	v_cndmask_b32_e32 v12, v18, v12, vcc
	v_ashrrev_i32_e32 v13, 31, v12
	v_mov_b32_e32 v14, s69
	v_sub_u32_e32 v18, 0, v14
	v_cndmask_b32_e32 v14, v18, v14, vcc
	v_ashrrev_i32_e32 v15, 31, v14
	global_load_dword v32, v[6:7], off
	global_load_dword v33, v[8:9], off
	v_lshl_add_u64 v[6:7], v[6:7], 0, v[12:13]
	v_lshl_add_u64 v[8:9], v[8:9], 0, v[12:13]
	global_load_dword v34, v[6:7], off
	global_load_dword v35, v[8:9], off
	v_lshl_add_u64 v[6:7], v[6:7], 0, v[12:13]
	v_lshl_add_u64 v[8:9], v[8:9], 0, v[12:13]
	global_load_dword v36, v[6:7], off
	global_load_dword v37, v[8:9], off
	v_lshl_add_u64 v[6:7], v[6:7], 0, v[12:13]
	v_lshl_add_u64 v[8:9], v[8:9], 0, v[12:13]
	global_load_dword v38, v[6:7], off
	global_load_dword v39, v[8:9], off
	v_lshl_add_u64 v[6:7], v[6:7], 0, v[12:13]
	v_lshl_add_u64 v[8:9], v[8:9], 0, v[12:13]
	global_load_dword v40, v[6:7], off
	global_load_dword v41, v[8:9], off
	v_lshl_add_u64 v[6:7], v[6:7], 0, v[12:13]
	v_lshl_add_u64 v[8:9], v[8:9], 0, v[12:13]
	global_load_dword v42, v[6:7], off
	global_load_dword v43, v[8:9], off
	v_lshl_add_u64 v[6:7], v[6:7], 0, v[12:13]
	v_lshl_add_u64 v[8:9], v[8:9], 0, v[12:13]
	global_load_dword v44, v[6:7], off
	global_load_dword v45, v[8:9], off
	v_lshl_add_u64 v[6:7], v[6:7], 0, v[12:13]
	v_lshl_add_u64 v[8:9], v[8:9], 0, v[12:13]
	global_load_dword v46, v[6:7], off
	global_load_dword v47, v[8:9], off
	v_lshl_add_u64 v[6:7], v[6:7], 0, v[12:13]
	v_lshl_add_u64 v[8:9], v[8:9], 0, v[12:13]
	global_load_dword v48, v[6:7], off
	global_load_dword v49, v[8:9], off
	v_lshl_add_u64 v[6:7], v[6:7], 0, v[12:13]
	v_lshl_add_u64 v[8:9], v[8:9], 0, v[12:13]
	global_load_dword v50, v[6:7], off
	global_load_dword v51, v[8:9], off
	v_lshl_add_u64 v[6:7], v[6:7], 0, v[12:13]
	v_lshl_add_u64 v[8:9], v[8:9], 0, v[12:13]
	global_load_dword v52, v[6:7], off
	global_load_dword v53, v[8:9], off
	v_lshl_add_u64 v[6:7], v[6:7], 0, v[12:13]
	v_lshl_add_u64 v[8:9], v[8:9], 0, v[12:13]
	global_load_dword v54, v[6:7], off
	global_load_dword v55, v[8:9], off
	v_lshl_add_u64 v[6:7], v[6:7], 0, v[12:13]
	v_lshl_add_u64 v[8:9], v[8:9], 0, v[12:13]
	global_load_dword v56, v[6:7], off
	global_load_dword v57, v[8:9], off
	v_lshl_add_u64 v[6:7], v[6:7], 0, v[12:13]
	v_lshl_add_u64 v[8:9], v[8:9], 0, v[12:13]
	global_load_dword v58, v[6:7], off
	global_load_dword v59, v[8:9], off
	v_lshl_add_u64 v[6:7], v[6:7], 0, v[12:13]
	v_lshl_add_u64 v[8:9], v[8:9], 0, v[12:13]
	global_load_dword v60, v[6:7], off
	global_load_dword v61, v[8:9], off
	v_lshl_add_u64 v[6:7], v[6:7], 0, v[12:13]
	v_lshl_add_u64 v[8:9], v[8:9], 0, v[12:13]
	global_load_dword v62, v[6:7], off
	global_load_dword v63, v[8:9], off
	v_lshl_add_u64 v[6:7], v[6:7], 0, v[12:13]
	v_lshl_add_u64 v[8:9], v[8:9], 0, v[12:13]
	global_load_dword v64, v[6:7], off
	global_load_dword v65, v[8:9], off
	v_lshl_add_u64 v[6:7], v[6:7], 0, v[12:13]
	v_lshl_add_u64 v[8:9], v[8:9], 0, v[12:13]
	global_load_dword v66, v[6:7], off
	global_load_dword v67, v[8:9], off
	v_lshl_add_u64 v[6:7], v[6:7], 0, v[12:13]
	v_lshl_add_u64 v[8:9], v[8:9], 0, v[12:13]
	global_load_dword v68, v[6:7], off
	global_load_dword v69, v[8:9], off
	v_lshl_add_u64 v[6:7], v[6:7], 0, v[12:13]
	v_lshl_add_u64 v[8:9], v[8:9], 0, v[12:13]
	global_load_dword v70, v[6:7], off
	global_load_dword v71, v[8:9], off
	v_lshl_add_u64 v[6:7], v[6:7], 0, v[12:13]
	v_lshl_add_u64 v[8:9], v[8:9], 0, v[12:13]
	global_load_dword v72, v[6:7], off
	global_load_dword v73, v[8:9], off
	v_lshl_add_u64 v[6:7], v[6:7], 0, v[12:13]
	v_lshl_add_u64 v[8:9], v[8:9], 0, v[12:13]
	s_waitcnt vmcnt(40)
	global_store_dword v[10:11], v5, off
	v_fma_f32 v5, v32, v5, v33
	v_lshl_add_u64 v[10:11], v[10:11], 0, v[14:15]
	global_load_dword v74, v[6:7], off
	global_load_dword v75, v[8:9], off
	v_lshl_add_u64 v[6:7], v[6:7], 0, v[12:13]
	v_lshl_add_u64 v[8:9], v[8:9], 0, v[12:13]
	s_waitcnt vmcnt(41)
	global_store_dword v[10:11], v5, off
	v_fma_f32 v5, v34, v5, v35
	v_lshl_add_u64 v[10:11], v[10:11], 0, v[14:15]
	global_load_dword v76, v[6:7], off
	global_load_dword v77, v[8:9], off
	v_lshl_add_u64 v[6:7], v[6:7], 0, v[12:13]
	v_lshl_add_u64 v[8:9], v[8:9], 0, v[12:13]
	s_waitcnt vmcnt(42)
	global_store_dword v[10:11], v5, off
	v_fma_f32 v5, v36, v5, v37
	v_lshl_add_u64 v[10:11], v[10:11], 0, v[14:15]
	global_load_dword v78, v[6:7], off
	global_load_dword v79, v[8:9], off
	v_lshl_add_u64 v[6:7], v[6:7], 0, v[12:13]
	v_lshl_add_u64 v[8:9], v[8:9], 0, v[12:13]
	s_waitcnt vmcnt(43)
	global_store_dword v[10:11], v5, off
	v_fma_f32 v5, v38, v5, v39
	v_lshl_add_u64 v[10:11], v[10:11], 0, v[14:15]
	global_load_dword v80, v[6:7], off
	global_load_dword v81, v[8:9], off
	v_lshl_add_u64 v[6:7], v[6:7], 0, v[12:13]
	v_lshl_add_u64 v[8:9], v[8:9], 0, v[12:13]
	s_waitcnt vmcnt(44)
	global_store_dword v[10:11], v5, off
	v_fma_f32 v5, v40, v5, v41
	v_lshl_add_u64 v[10:11], v[10:11], 0, v[14:15]
	global_load_dword v82, v[6:7], off
	global_load_dword v83, v[8:9], off
	v_lshl_add_u64 v[6:7], v[6:7], 0, v[12:13]
	v_lshl_add_u64 v[8:9], v[8:9], 0, v[12:13]
	s_waitcnt vmcnt(45)
	global_store_dword v[10:11], v5, off
	v_fma_f32 v5, v42, v5, v43
	v_lshl_add_u64 v[10:11], v[10:11], 0, v[14:15]
	global_load_dword v84, v[6:7], off
	global_load_dword v85, v[8:9], off
	v_lshl_add_u64 v[6:7], v[6:7], 0, v[12:13]
	v_lshl_add_u64 v[8:9], v[8:9], 0, v[12:13]
	s_waitcnt vmcnt(46)
	global_store_dword v[10:11], v5, off
	v_fma_f32 v5, v44, v5, v45
	v_lshl_add_u64 v[10:11], v[10:11], 0, v[14:15]
	global_load_dword v86, v[6:7], off
	global_load_dword v87, v[8:9], off
	v_lshl_add_u64 v[6:7], v[6:7], 0, v[12:13]
	v_lshl_add_u64 v[8:9], v[8:9], 0, v[12:13]
	s_waitcnt vmcnt(47)
	global_store_dword v[10:11], v5, off
	v_fma_f32 v5, v46, v5, v47
	v_lshl_add_u64 v[10:11], v[10:11], 0, v[14:15]
	global_load_dword v88, v[6:7], off
	global_load_dword v89, v[8:9], off
	v_lshl_add_u64 v[6:7], v[6:7], 0, v[12:13]
	v_lshl_add_u64 v[8:9], v[8:9], 0, v[12:13]
	s_waitcnt vmcnt(48)
	global_store_dword v[10:11], v5, off
	v_fma_f32 v5, v48, v5, v49
	v_lshl_add_u64 v[10:11], v[10:11], 0, v[14:15]
	global_load_dword v90, v[6:7], off
	global_load_dword v91, v[8:9], off
	v_lshl_add_u64 v[6:7], v[6:7], 0, v[12:13]
	v_lshl_add_u64 v[8:9], v[8:9], 0, v[12:13]
	s_waitcnt vmcnt(49)
	global_store_dword v[10:11], v5, off
	v_fma_f32 v5, v50, v5, v51
	v_lshl_add_u64 v[10:11], v[10:11], 0, v[14:15]
	global_load_dword v92, v[6:7], off
	global_load_dword v93, v[8:9], off
	v_lshl_add_u64 v[6:7], v[6:7], 0, v[12:13]
	v_lshl_add_u64 v[8:9], v[8:9], 0, v[12:13]
	s_waitcnt vmcnt(50)
	global_store_dword v[10:11], v5, off
	v_fma_f32 v5, v52, v5, v53
	v_lshl_add_u64 v[10:11], v[10:11], 0, v[14:15]
	global_load_dword v94, v[6:7], off
	global_load_dword v95, v[8:9], off
	v_lshl_add_u64 v[6:7], v[6:7], 0, v[12:13]
	v_lshl_add_u64 v[8:9], v[8:9], 0, v[12:13]
	s_waitcnt vmcnt(51)
	global_store_dword v[10:11], v5, off
	v_fma_f32 v5, v54, v5, v55
	v_lshl_add_u64 v[10:11], v[10:11], 0, v[14:15]
	global_load_dword v32, v[6:7], off
	global_load_dword v33, v[8:9], off
	v_lshl_add_u64 v[6:7], v[6:7], 0, v[12:13]
	v_lshl_add_u64 v[8:9], v[8:9], 0, v[12:13]
	s_waitcnt vmcnt(52)
	global_store_dword v[10:11], v5, off
	v_fma_f32 v5, v56, v5, v57
	v_lshl_add_u64 v[10:11], v[10:11], 0, v[14:15]
	global_load_dword v34, v[6:7], off
	global_load_dword v35, v[8:9], off
	v_lshl_add_u64 v[6:7], v[6:7], 0, v[12:13]
	v_lshl_add_u64 v[8:9], v[8:9], 0, v[12:13]
	s_waitcnt vmcnt(53)
	global_store_dword v[10:11], v5, off
	v_fma_f32 v5, v58, v5, v59
	v_lshl_add_u64 v[10:11], v[10:11], 0, v[14:15]
	global_load_dword v36, v[6:7], off
	global_load_dword v37, v[8:9], off
	v_lshl_add_u64 v[6:7], v[6:7], 0, v[12:13]
	v_lshl_add_u64 v[8:9], v[8:9], 0, v[12:13]
	s_waitcnt vmcnt(54)
	global_store_dword v[10:11], v5, off
	v_fma_f32 v5, v60, v5, v61
	v_lshl_add_u64 v[10:11], v[10:11], 0, v[14:15]
	global_load_dword v38, v[6:7], off
	global_load_dword v39, v[8:9], off
	v_lshl_add_u64 v[6:7], v[6:7], 0, v[12:13]
	v_lshl_add_u64 v[8:9], v[8:9], 0, v[12:13]
	s_waitcnt vmcnt(55)
	global_store_dword v[10:11], v5, off
	v_fma_f32 v5, v62, v5, v63
	v_lshl_add_u64 v[10:11], v[10:11], 0, v[14:15]
	global_load_dword v40, v[6:7], off
	global_load_dword v41, v[8:9], off
	v_lshl_add_u64 v[6:7], v[6:7], 0, v[12:13]
	v_lshl_add_u64 v[8:9], v[8:9], 0, v[12:13]
	s_waitcnt vmcnt(56)
	global_store_dword v[10:11], v5, off
	v_fma_f32 v5, v64, v5, v65
	v_lshl_add_u64 v[10:11], v[10:11], 0, v[14:15]
	global_load_dword v42, v[6:7], off
	global_load_dword v43, v[8:9], off
	v_lshl_add_u64 v[6:7], v[6:7], 0, v[12:13]
	v_lshl_add_u64 v[8:9], v[8:9], 0, v[12:13]
	s_waitcnt vmcnt(57)
	global_store_dword v[10:11], v5, off
	v_fma_f32 v5, v66, v5, v67
	v_lshl_add_u64 v[10:11], v[10:11], 0, v[14:15]
	global_load_dword v44, v[6:7], off
	global_load_dword v45, v[8:9], off
	v_lshl_add_u64 v[6:7], v[6:7], 0, v[12:13]
	v_lshl_add_u64 v[8:9], v[8:9], 0, v[12:13]
	s_waitcnt vmcnt(58)
	global_store_dword v[10:11], v5, off
	v_fma_f32 v5, v68, v5, v69
	v_lshl_add_u64 v[10:11], v[10:11], 0, v[14:15]
	global_load_dword v46, v[6:7], off
	global_load_dword v47, v[8:9], off
	v_lshl_add_u64 v[6:7], v[6:7], 0, v[12:13]
	v_lshl_add_u64 v[8:9], v[8:9], 0, v[12:13]
	s_waitcnt vmcnt(59)
	global_store_dword v[10:11], v5, off
	v_fma_f32 v5, v70, v5, v71
	v_lshl_add_u64 v[10:11], v[10:11], 0, v[14:15]
	global_load_dword v48, v[6:7], off
	global_load_dword v49, v[8:9], off
	v_lshl_add_u64 v[6:7], v[6:7], 0, v[12:13]
	v_lshl_add_u64 v[8:9], v[8:9], 0, v[12:13]
	s_waitcnt vmcnt(60)
	global_store_dword v[10:11], v5, off
	v_fma_f32 v5, v72, v5, v73
	v_lshl_add_u64 v[10:11], v[10:11], 0, v[14:15]
	global_load_dword v50, v[6:7], off
	global_load_dword v51, v[8:9], off
	v_lshl_add_u64 v[6:7], v[6:7], 0, v[12:13]
	v_lshl_add_u64 v[8:9], v[8:9], 0, v[12:13]
	s_waitcnt vmcnt(60)
	global_store_dword v[10:11], v5, off
	v_fma_f32 v5, v74, v5, v75
	v_lshl_add_u64 v[10:11], v[10:11], 0, v[14:15]
	global_load_dword v52, v[6:7], off
	global_load_dword v53, v[8:9], off
	v_lshl_add_u64 v[6:7], v[6:7], 0, v[12:13]
	v_lshl_add_u64 v[8:9], v[8:9], 0, v[12:13]
	s_waitcnt vmcnt(60)
	global_store_dword v[10:11], v5, off
	v_fma_f32 v5, v76, v5, v77
	v_lshl_add_u64 v[10:11], v[10:11], 0, v[14:15]
	global_load_dword v54, v[6:7], off
	global_load_dword v55, v[8:9], off
	v_lshl_add_u64 v[6:7], v[6:7], 0, v[12:13]
	v_lshl_add_u64 v[8:9], v[8:9], 0, v[12:13]
	s_waitcnt vmcnt(60)
	global_store_dword v[10:11], v5, off
	v_fma_f32 v5, v78, v5, v79
	v_lshl_add_u64 v[10:11], v[10:11], 0, v[14:15]
	global_load_dword v56, v[6:7], off
	global_load_dword v57, v[8:9], off
	v_lshl_add_u64 v[6:7], v[6:7], 0, v[12:13]
	v_lshl_add_u64 v[8:9], v[8:9], 0, v[12:13]
	s_waitcnt vmcnt(60)
	global_store_dword v[10:11], v5, off
	v_fma_f32 v5, v80, v5, v81
	v_lshl_add_u64 v[10:11], v[10:11], 0, v[14:15]
	global_load_dword v58, v[6:7], off
	global_load_dword v59, v[8:9], off
	v_lshl_add_u64 v[6:7], v[6:7], 0, v[12:13]
	v_lshl_add_u64 v[8:9], v[8:9], 0, v[12:13]
	s_waitcnt vmcnt(60)
	global_store_dword v[10:11], v5, off
	v_fma_f32 v5, v82, v5, v83
	v_lshl_add_u64 v[10:11], v[10:11], 0, v[14:15]
	global_load_dword v60, v[6:7], off
	global_load_dword v61, v[8:9], off
	v_lshl_add_u64 v[6:7], v[6:7], 0, v[12:13]
	v_lshl_add_u64 v[8:9], v[8:9], 0, v[12:13]
	s_waitcnt vmcnt(60)
	global_store_dword v[10:11], v5, off
	v_fma_f32 v5, v84, v5, v85
	v_lshl_add_u64 v[10:11], v[10:11], 0, v[14:15]
	global_load_dword v62, v[6:7], off
	global_load_dword v63, v[8:9], off
	v_lshl_add_u64 v[6:7], v[6:7], 0, v[12:13]
	v_lshl_add_u64 v[8:9], v[8:9], 0, v[12:13]
	s_waitcnt vmcnt(60)
	global_store_dword v[10:11], v5, off
	v_fma_f32 v5, v86, v5, v87
	v_lshl_add_u64 v[10:11], v[10:11], 0, v[14:15]
	global_load_dword v64, v[6:7], off
	global_load_dword v65, v[8:9], off
	v_lshl_add_u64 v[6:7], v[6:7], 0, v[12:13]
	v_lshl_add_u64 v[8:9], v[8:9], 0, v[12:13]
	s_waitcnt vmcnt(60)
	global_store_dword v[10:11], v5, off
	v_fma_f32 v5, v88, v5, v89
	v_lshl_add_u64 v[10:11], v[10:11], 0, v[14:15]
	global_load_dword v66, v[6:7], off
	global_load_dword v67, v[8:9], off
	v_lshl_add_u64 v[6:7], v[6:7], 0, v[12:13]
	v_lshl_add_u64 v[8:9], v[8:9], 0, v[12:13]
	s_waitcnt vmcnt(60)
	global_store_dword v[10:11], v5, off
	v_fma_f32 v5, v90, v5, v91
	v_lshl_add_u64 v[10:11], v[10:11], 0, v[14:15]
	global_load_dword v68, v[6:7], off
	global_load_dword v69, v[8:9], off
	v_lshl_add_u64 v[6:7], v[6:7], 0, v[12:13]
	v_lshl_add_u64 v[8:9], v[8:9], 0, v[12:13]
	s_waitcnt vmcnt(60)
	global_store_dword v[10:11], v5, off
	v_fma_f32 v5, v92, v5, v93
	v_lshl_add_u64 v[10:11], v[10:11], 0, v[14:15]
	global_load_dword v70, v[6:7], off
	global_load_dword v71, v[8:9], off
	v_lshl_add_u64 v[6:7], v[6:7], 0, v[12:13]
	v_lshl_add_u64 v[8:9], v[8:9], 0, v[12:13]
	s_waitcnt vmcnt(60)
	global_store_dword v[10:11], v5, off
	v_fma_f32 v5, v94, v5, v95
	v_lshl_add_u64 v[10:11], v[10:11], 0, v[14:15]
	global_load_dword v72, v[6:7], off
	global_load_dword v73, v[8:9], off
	v_lshl_add_u64 v[6:7], v[6:7], 0, v[12:13]
	v_lshl_add_u64 v[8:9], v[8:9], 0, v[12:13]
	s_waitcnt vmcnt(60)
	global_store_dword v[10:11], v5, off
	v_fma_f32 v5, v32, v5, v33
	v_lshl_add_u64 v[10:11], v[10:11], 0, v[14:15]
	global_load_dword v74, v[6:7], off
	global_load_dword v75, v[8:9], off
	v_lshl_add_u64 v[6:7], v[6:7], 0, v[12:13]
	v_lshl_add_u64 v[8:9], v[8:9], 0, v[12:13]
	s_waitcnt vmcnt(60)
	global_store_dword v[10:11], v5, off
	v_fma_f32 v5, v34, v5, v35
	v_lshl_add_u64 v[10:11], v[10:11], 0, v[14:15]
	global_load_dword v76, v[6:7], off
	global_load_dword v77, v[8:9], off
	v_lshl_add_u64 v[6:7], v[6:7], 0, v[12:13]
	v_lshl_add_u64 v[8:9], v[8:9], 0, v[12:13]
	s_waitcnt vmcnt(60)
	global_store_dword v[10:11], v5, off
	v_fma_f32 v5, v36, v5, v37
	v_lshl_add_u64 v[10:11], v[10:11], 0, v[14:15]
	global_load_dword v78, v[6:7], off
	global_load_dword v79, v[8:9], off
	v_lshl_add_u64 v[6:7], v[6:7], 0, v[12:13]
	v_lshl_add_u64 v[8:9], v[8:9], 0, v[12:13]
	s_waitcnt vmcnt(60)
	global_store_dword v[10:11], v5, off
	v_fma_f32 v5, v38, v5, v39
	v_lshl_add_u64 v[10:11], v[10:11], 0, v[14:15]
	global_load_dword v80, v[6:7], off
	global_load_dword v81, v[8:9], off
	v_lshl_add_u64 v[6:7], v[6:7], 0, v[12:13]
	v_lshl_add_u64 v[8:9], v[8:9], 0, v[12:13]
	s_waitcnt vmcnt(60)
	global_store_dword v[10:11], v5, off
	v_fma_f32 v5, v40, v5, v41
	v_lshl_add_u64 v[10:11], v[10:11], 0, v[14:15]
	global_load_dword v82, v[6:7], off
	global_load_dword v83, v[8:9], off
	v_lshl_add_u64 v[6:7], v[6:7], 0, v[12:13]
	v_lshl_add_u64 v[8:9], v[8:9], 0, v[12:13]
	s_waitcnt vmcnt(60)
	global_store_dword v[10:11], v5, off
	v_fma_f32 v5, v42, v5, v43
	v_lshl_add_u64 v[10:11], v[10:11], 0, v[14:15]
	global_load_dword v84, v[6:7], off
	global_load_dword v85, v[8:9], off
	v_lshl_add_u64 v[6:7], v[6:7], 0, v[12:13]
	v_lshl_add_u64 v[8:9], v[8:9], 0, v[12:13]
	s_waitcnt vmcnt(60)
	global_store_dword v[10:11], v5, off
	v_fma_f32 v5, v44, v5, v45
	v_lshl_add_u64 v[10:11], v[10:11], 0, v[14:15]
	global_load_dword v86, v[6:7], off
	global_load_dword v87, v[8:9], off
	v_lshl_add_u64 v[6:7], v[6:7], 0, v[12:13]
	v_lshl_add_u64 v[8:9], v[8:9], 0, v[12:13]
	s_waitcnt vmcnt(60)
	global_store_dword v[10:11], v5, off
	v_fma_f32 v5, v46, v5, v47
	v_lshl_add_u64 v[10:11], v[10:11], 0, v[14:15]
	global_load_dword v88, v[6:7], off
	global_load_dword v89, v[8:9], off
	v_lshl_add_u64 v[6:7], v[6:7], 0, v[12:13]
	v_lshl_add_u64 v[8:9], v[8:9], 0, v[12:13]
	s_waitcnt vmcnt(60)
	global_store_dword v[10:11], v5, off
	v_fma_f32 v5, v48, v5, v49
	v_lshl_add_u64 v[10:11], v[10:11], 0, v[14:15]
	global_load_dword v90, v[6:7], off
	global_load_dword v91, v[8:9], off
	v_lshl_add_u64 v[6:7], v[6:7], 0, v[12:13]
	v_lshl_add_u64 v[8:9], v[8:9], 0, v[12:13]
	s_waitcnt vmcnt(60)
	global_store_dword v[10:11], v5, off
	v_fma_f32 v5, v50, v5, v51
	v_lshl_add_u64 v[10:11], v[10:11], 0, v[14:15]
	global_load_dword v92, v[6:7], off
	global_load_dword v93, v[8:9], off
	v_lshl_add_u64 v[6:7], v[6:7], 0, v[12:13]
	v_lshl_add_u64 v[8:9], v[8:9], 0, v[12:13]
	s_waitcnt vmcnt(60)
	global_store_dword v[10:11], v5, off
	v_fma_f32 v5, v52, v5, v53
	v_lshl_add_u64 v[10:11], v[10:11], 0, v[14:15]
	global_load_dword v94, v[6:7], off
	global_load_dword v95, v[8:9], off
	v_lshl_add_u64 v[6:7], v[6:7], 0, v[12:13]
	v_lshl_add_u64 v[8:9], v[8:9], 0, v[12:13]
	s_waitcnt vmcnt(60)
	global_store_dword v[10:11], v5, off
	v_fma_f32 v5, v54, v5, v55
	v_lshl_add_u64 v[10:11], v[10:11], 0, v[14:15]
	global_load_dword v32, v[6:7], off
	global_load_dword v33, v[8:9], off
	v_lshl_add_u64 v[6:7], v[6:7], 0, v[12:13]
	v_lshl_add_u64 v[8:9], v[8:9], 0, v[12:13]
	s_waitcnt vmcnt(60)
	global_store_dword v[10:11], v5, off
	v_fma_f32 v5, v56, v5, v57
	v_lshl_add_u64 v[10:11], v[10:11], 0, v[14:15]
	global_load_dword v34, v[6:7], off
	global_load_dword v35, v[8:9], off
	v_lshl_add_u64 v[6:7], v[6:7], 0, v[12:13]
	v_lshl_add_u64 v[8:9], v[8:9], 0, v[12:13]
	s_waitcnt vmcnt(60)
	global_store_dword v[10:11], v5, off
	v_fma_f32 v5, v58, v5, v59
	v_lshl_add_u64 v[10:11], v[10:11], 0, v[14:15]
	global_load_dword v36, v[6:7], off
	global_load_dword v37, v[8:9], off
	v_lshl_add_u64 v[6:7], v[6:7], 0, v[12:13]
	v_lshl_add_u64 v[8:9], v[8:9], 0, v[12:13]
	s_waitcnt vmcnt(60)
	global_store_dword v[10:11], v5, off
	v_fma_f32 v5, v60, v5, v61
	v_lshl_add_u64 v[10:11], v[10:11], 0, v[14:15]
	global_load_dword v38, v[6:7], off
	global_load_dword v39, v[8:9], off
	v_lshl_add_u64 v[6:7], v[6:7], 0, v[12:13]
	v_lshl_add_u64 v[8:9], v[8:9], 0, v[12:13]
	s_waitcnt vmcnt(60)
	global_store_dword v[10:11], v5, off
	v_fma_f32 v5, v62, v5, v63
	v_lshl_add_u64 v[10:11], v[10:11], 0, v[14:15]
	global_load_dword v40, v[6:7], off
	global_load_dword v41, v[8:9], off
	v_lshl_add_u64 v[6:7], v[6:7], 0, v[12:13]
	v_lshl_add_u64 v[8:9], v[8:9], 0, v[12:13]
	s_waitcnt vmcnt(60)
	global_store_dword v[10:11], v5, off
	v_fma_f32 v5, v64, v5, v65
	v_lshl_add_u64 v[10:11], v[10:11], 0, v[14:15]
	global_load_dword v42, v[6:7], off
	global_load_dword v43, v[8:9], off
	v_lshl_add_u64 v[6:7], v[6:7], 0, v[12:13]
	v_lshl_add_u64 v[8:9], v[8:9], 0, v[12:13]
	s_waitcnt vmcnt(60)
	global_store_dword v[10:11], v5, off
	v_fma_f32 v5, v66, v5, v67
	v_lshl_add_u64 v[10:11], v[10:11], 0, v[14:15]
	global_load_dword v44, v[6:7], off
	global_load_dword v45, v[8:9], off
	v_lshl_add_u64 v[6:7], v[6:7], 0, v[12:13]
	v_lshl_add_u64 v[8:9], v[8:9], 0, v[12:13]
	s_waitcnt vmcnt(60)
	global_store_dword v[10:11], v5, off
	v_fma_f32 v5, v68, v5, v69
	v_lshl_add_u64 v[10:11], v[10:11], 0, v[14:15]
	global_load_dword v46, v[6:7], off
	global_load_dword v47, v[8:9], off
	v_lshl_add_u64 v[6:7], v[6:7], 0, v[12:13]
	v_lshl_add_u64 v[8:9], v[8:9], 0, v[12:13]
	s_waitcnt vmcnt(60)
	global_store_dword v[10:11], v5, off
	v_fma_f32 v5, v70, v5, v71
	v_lshl_add_u64 v[10:11], v[10:11], 0, v[14:15]
	global_load_dword v48, v[6:7], off
	global_load_dword v49, v[8:9], off
	v_lshl_add_u64 v[6:7], v[6:7], 0, v[12:13]
	v_lshl_add_u64 v[8:9], v[8:9], 0, v[12:13]
	s_waitcnt vmcnt(60)
	global_store_dword v[10:11], v5, off
	v_fma_f32 v5, v72, v5, v73
	v_lshl_add_u64 v[10:11], v[10:11], 0, v[14:15]
	global_load_dword v50, v[6:7], off
	global_load_dword v51, v[8:9], off
	v_lshl_add_u64 v[6:7], v[6:7], 0, v[12:13]
	v_lshl_add_u64 v[8:9], v[8:9], 0, v[12:13]
	s_waitcnt vmcnt(60)
	global_store_dword v[10:11], v5, off
	v_fma_f32 v5, v74, v5, v75
	v_lshl_add_u64 v[10:11], v[10:11], 0, v[14:15]
	global_load_dword v52, v[6:7], off
	global_load_dword v53, v[8:9], off
	v_lshl_add_u64 v[6:7], v[6:7], 0, v[12:13]
	v_lshl_add_u64 v[8:9], v[8:9], 0, v[12:13]
	s_waitcnt vmcnt(60)
	global_store_dword v[10:11], v5, off
	v_fma_f32 v5, v76, v5, v77
	v_lshl_add_u64 v[10:11], v[10:11], 0, v[14:15]
	global_load_dword v54, v[6:7], off
	global_load_dword v55, v[8:9], off
	v_lshl_add_u64 v[6:7], v[6:7], 0, v[12:13]
	v_lshl_add_u64 v[8:9], v[8:9], 0, v[12:13]
	s_waitcnt vmcnt(60)
	global_store_dword v[10:11], v5, off
	v_fma_f32 v5, v78, v5, v79
	v_lshl_add_u64 v[10:11], v[10:11], 0, v[14:15]
	global_load_dword v56, v[6:7], off
	global_load_dword v57, v[8:9], off
	v_lshl_add_u64 v[6:7], v[6:7], 0, v[12:13]
	v_lshl_add_u64 v[8:9], v[8:9], 0, v[12:13]
	s_waitcnt vmcnt(60)
	global_store_dword v[10:11], v5, off
	v_fma_f32 v5, v80, v5, v81
	v_lshl_add_u64 v[10:11], v[10:11], 0, v[14:15]
	global_load_dword v58, v[6:7], off
	global_load_dword v59, v[8:9], off
	v_lshl_add_u64 v[6:7], v[6:7], 0, v[12:13]
	v_lshl_add_u64 v[8:9], v[8:9], 0, v[12:13]
	s_waitcnt vmcnt(60)
	global_store_dword v[10:11], v5, off
	v_fma_f32 v5, v82, v5, v83
	v_lshl_add_u64 v[10:11], v[10:11], 0, v[14:15]
	global_load_dword v60, v[6:7], off
	global_load_dword v61, v[8:9], off
	v_lshl_add_u64 v[6:7], v[6:7], 0, v[12:13]
	v_lshl_add_u64 v[8:9], v[8:9], 0, v[12:13]
	s_waitcnt vmcnt(60)
	global_store_dword v[10:11], v5, off
	v_fma_f32 v5, v84, v5, v85
	v_lshl_add_u64 v[10:11], v[10:11], 0, v[14:15]
	global_load_dword v62, v[6:7], off
	global_load_dword v63, v[8:9], off
	v_lshl_add_u64 v[6:7], v[6:7], 0, v[12:13]
	v_lshl_add_u64 v[8:9], v[8:9], 0, v[12:13]
	s_waitcnt vmcnt(60)
	global_store_dword v[10:11], v5, off
	v_fma_f32 v5, v86, v5, v87
	v_lshl_add_u64 v[10:11], v[10:11], 0, v[14:15]
	global_load_dword v64, v[6:7], off
	global_load_dword v65, v[8:9], off
	v_lshl_add_u64 v[6:7], v[6:7], 0, v[12:13]
	v_lshl_add_u64 v[8:9], v[8:9], 0, v[12:13]
	s_waitcnt vmcnt(60)
	global_store_dword v[10:11], v5, off
	v_fma_f32 v5, v88, v5, v89
	v_lshl_add_u64 v[10:11], v[10:11], 0, v[14:15]
	global_load_dword v66, v[6:7], off
	global_load_dword v67, v[8:9], off
	v_lshl_add_u64 v[6:7], v[6:7], 0, v[12:13]
	v_lshl_add_u64 v[8:9], v[8:9], 0, v[12:13]
	s_waitcnt vmcnt(60)
	global_store_dword v[10:11], v5, off
	v_fma_f32 v5, v90, v5, v91
	v_lshl_add_u64 v[10:11], v[10:11], 0, v[14:15]
	global_load_dword v68, v[6:7], off
	global_load_dword v69, v[8:9], off
	v_lshl_add_u64 v[6:7], v[6:7], 0, v[12:13]
	v_lshl_add_u64 v[8:9], v[8:9], 0, v[12:13]
	s_waitcnt vmcnt(60)
	global_store_dword v[10:11], v5, off
	v_fma_f32 v5, v92, v5, v93
	v_lshl_add_u64 v[10:11], v[10:11], 0, v[14:15]
	global_load_dword v70, v[6:7], off
	global_load_dword v71, v[8:9], off
	v_lshl_add_u64 v[6:7], v[6:7], 0, v[12:13]
	v_lshl_add_u64 v[8:9], v[8:9], 0, v[12:13]
	s_waitcnt vmcnt(60)
	global_store_dword v[10:11], v5, off
	v_fma_f32 v5, v94, v5, v95
	v_lshl_add_u64 v[10:11], v[10:11], 0, v[14:15]
	global_load_dword v72, v[6:7], off
	global_load_dword v73, v[8:9], off
	v_lshl_add_u64 v[6:7], v[6:7], 0, v[12:13]
	v_lshl_add_u64 v[8:9], v[8:9], 0, v[12:13]
	s_waitcnt vmcnt(60)
	global_store_dword v[10:11], v5, off
	v_fma_f32 v5, v32, v5, v33
	v_lshl_add_u64 v[10:11], v[10:11], 0, v[14:15]
	global_load_dword v74, v[6:7], off
	global_load_dword v75, v[8:9], off
	v_lshl_add_u64 v[6:7], v[6:7], 0, v[12:13]
	v_lshl_add_u64 v[8:9], v[8:9], 0, v[12:13]
	s_waitcnt vmcnt(60)
	global_store_dword v[10:11], v5, off
	v_fma_f32 v5, v34, v5, v35
	v_lshl_add_u64 v[10:11], v[10:11], 0, v[14:15]
	global_load_dword v76, v[6:7], off
	global_load_dword v77, v[8:9], off
	v_lshl_add_u64 v[6:7], v[6:7], 0, v[12:13]
	v_lshl_add_u64 v[8:9], v[8:9], 0, v[12:13]
	s_waitcnt vmcnt(60)
	global_store_dword v[10:11], v5, off
	v_fma_f32 v5, v36, v5, v37
	v_lshl_add_u64 v[10:11], v[10:11], 0, v[14:15]
	global_load_dword v78, v[6:7], off
	global_load_dword v79, v[8:9], off
	v_lshl_add_u64 v[6:7], v[6:7], 0, v[12:13]
	v_lshl_add_u64 v[8:9], v[8:9], 0, v[12:13]
	s_waitcnt vmcnt(60)
	global_store_dword v[10:11], v5, off
	v_fma_f32 v5, v38, v5, v39
	v_lshl_add_u64 v[10:11], v[10:11], 0, v[14:15]
	global_load_dword v80, v[6:7], off
	global_load_dword v81, v[8:9], off
	v_lshl_add_u64 v[6:7], v[6:7], 0, v[12:13]
	v_lshl_add_u64 v[8:9], v[8:9], 0, v[12:13]
	s_waitcnt vmcnt(60)
	global_store_dword v[10:11], v5, off
	v_fma_f32 v5, v40, v5, v41
	v_lshl_add_u64 v[10:11], v[10:11], 0, v[14:15]
	global_load_dword v82, v[6:7], off
	global_load_dword v83, v[8:9], off
	v_lshl_add_u64 v[6:7], v[6:7], 0, v[12:13]
	v_lshl_add_u64 v[8:9], v[8:9], 0, v[12:13]
	s_waitcnt vmcnt(60)
	global_store_dword v[10:11], v5, off
	v_fma_f32 v5, v42, v5, v43
	v_lshl_add_u64 v[10:11], v[10:11], 0, v[14:15]
	global_load_dword v84, v[6:7], off
	global_load_dword v85, v[8:9], off
	v_lshl_add_u64 v[6:7], v[6:7], 0, v[12:13]
	v_lshl_add_u64 v[8:9], v[8:9], 0, v[12:13]
	s_waitcnt vmcnt(60)
	global_store_dword v[10:11], v5, off
	v_fma_f32 v5, v44, v5, v45
	v_lshl_add_u64 v[10:11], v[10:11], 0, v[14:15]
	global_load_dword v86, v[6:7], off
	global_load_dword v87, v[8:9], off
	v_lshl_add_u64 v[6:7], v[6:7], 0, v[12:13]
	v_lshl_add_u64 v[8:9], v[8:9], 0, v[12:13]
	s_waitcnt vmcnt(60)
	global_store_dword v[10:11], v5, off
	v_fma_f32 v5, v46, v5, v47
	v_lshl_add_u64 v[10:11], v[10:11], 0, v[14:15]
	global_load_dword v88, v[6:7], off
	global_load_dword v89, v[8:9], off
	v_lshl_add_u64 v[6:7], v[6:7], 0, v[12:13]
	v_lshl_add_u64 v[8:9], v[8:9], 0, v[12:13]
	s_waitcnt vmcnt(60)
	global_store_dword v[10:11], v5, off
	v_fma_f32 v5, v48, v5, v49
	v_lshl_add_u64 v[10:11], v[10:11], 0, v[14:15]
	global_load_dword v90, v[6:7], off
	global_load_dword v91, v[8:9], off
	v_lshl_add_u64 v[6:7], v[6:7], 0, v[12:13]
	v_lshl_add_u64 v[8:9], v[8:9], 0, v[12:13]
	s_waitcnt vmcnt(60)
	global_store_dword v[10:11], v5, off
	v_fma_f32 v5, v50, v5, v51
	v_lshl_add_u64 v[10:11], v[10:11], 0, v[14:15]
	global_load_dword v92, v[6:7], off
	global_load_dword v93, v[8:9], off
	v_lshl_add_u64 v[6:7], v[6:7], 0, v[12:13]
	v_lshl_add_u64 v[8:9], v[8:9], 0, v[12:13]
	s_waitcnt vmcnt(60)
	global_store_dword v[10:11], v5, off
	v_fma_f32 v5, v52, v5, v53
	v_lshl_add_u64 v[10:11], v[10:11], 0, v[14:15]
	global_load_dword v94, v[6:7], off
	global_load_dword v95, v[8:9], off
	v_lshl_add_u64 v[6:7], v[6:7], 0, v[12:13]
	v_lshl_add_u64 v[8:9], v[8:9], 0, v[12:13]
	s_waitcnt vmcnt(60)
	global_store_dword v[10:11], v5, off
	v_fma_f32 v5, v54, v5, v55
	v_lshl_add_u64 v[10:11], v[10:11], 0, v[14:15]
	global_load_dword v32, v[6:7], off
	global_load_dword v33, v[8:9], off
	v_lshl_add_u64 v[6:7], v[6:7], 0, v[12:13]
	v_lshl_add_u64 v[8:9], v[8:9], 0, v[12:13]
	s_waitcnt vmcnt(60)
	global_store_dword v[10:11], v5, off
	v_fma_f32 v5, v56, v5, v57
	v_lshl_add_u64 v[10:11], v[10:11], 0, v[14:15]
	global_load_dword v34, v[6:7], off
	global_load_dword v35, v[8:9], off
	v_lshl_add_u64 v[6:7], v[6:7], 0, v[12:13]
	v_lshl_add_u64 v[8:9], v[8:9], 0, v[12:13]
	s_waitcnt vmcnt(60)
	global_store_dword v[10:11], v5, off
	v_fma_f32 v5, v58, v5, v59
	v_lshl_add_u64 v[10:11], v[10:11], 0, v[14:15]
	global_load_dword v36, v[6:7], off
	global_load_dword v37, v[8:9], off
	v_lshl_add_u64 v[6:7], v[6:7], 0, v[12:13]
	v_lshl_add_u64 v[8:9], v[8:9], 0, v[12:13]
	s_waitcnt vmcnt(60)
	global_store_dword v[10:11], v5, off
	v_fma_f32 v5, v60, v5, v61
	v_lshl_add_u64 v[10:11], v[10:11], 0, v[14:15]
	global_load_dword v38, v[6:7], off
	global_load_dword v39, v[8:9], off
	v_lshl_add_u64 v[6:7], v[6:7], 0, v[12:13]
	v_lshl_add_u64 v[8:9], v[8:9], 0, v[12:13]
	s_waitcnt vmcnt(60)
	global_store_dword v[10:11], v5, off
	v_fma_f32 v5, v62, v5, v63
	v_lshl_add_u64 v[10:11], v[10:11], 0, v[14:15]
	global_load_dword v40, v[6:7], off
	global_load_dword v41, v[8:9], off
	v_lshl_add_u64 v[6:7], v[6:7], 0, v[12:13]
	v_lshl_add_u64 v[8:9], v[8:9], 0, v[12:13]
	s_waitcnt vmcnt(60)
	global_store_dword v[10:11], v5, off
	v_fma_f32 v5, v64, v5, v65
	v_lshl_add_u64 v[10:11], v[10:11], 0, v[14:15]
	global_load_dword v42, v[6:7], off
	global_load_dword v43, v[8:9], off
	v_lshl_add_u64 v[6:7], v[6:7], 0, v[12:13]
	v_lshl_add_u64 v[8:9], v[8:9], 0, v[12:13]
	s_waitcnt vmcnt(60)
	global_store_dword v[10:11], v5, off
	v_fma_f32 v5, v66, v5, v67
	v_lshl_add_u64 v[10:11], v[10:11], 0, v[14:15]
	global_load_dword v44, v[6:7], off
	global_load_dword v45, v[8:9], off
	v_lshl_add_u64 v[6:7], v[6:7], 0, v[12:13]
	v_lshl_add_u64 v[8:9], v[8:9], 0, v[12:13]
	s_waitcnt vmcnt(60)
	global_store_dword v[10:11], v5, off
	v_fma_f32 v5, v68, v5, v69
	v_lshl_add_u64 v[10:11], v[10:11], 0, v[14:15]
	global_load_dword v46, v[6:7], off
	global_load_dword v47, v[8:9], off
	v_lshl_add_u64 v[6:7], v[6:7], 0, v[12:13]
	v_lshl_add_u64 v[8:9], v[8:9], 0, v[12:13]
	s_waitcnt vmcnt(60)
	global_store_dword v[10:11], v5, off
	v_fma_f32 v5, v70, v5, v71
	v_lshl_add_u64 v[10:11], v[10:11], 0, v[14:15]
	global_load_dword v48, v[6:7], off
	global_load_dword v49, v[8:9], off
	v_lshl_add_u64 v[6:7], v[6:7], 0, v[12:13]
	v_lshl_add_u64 v[8:9], v[8:9], 0, v[12:13]
	s_waitcnt vmcnt(60)
	global_store_dword v[10:11], v5, off
	v_fma_f32 v5, v72, v5, v73
	v_lshl_add_u64 v[10:11], v[10:11], 0, v[14:15]
	global_load_dword v50, v[6:7], off
	global_load_dword v51, v[8:9], off
	v_lshl_add_u64 v[6:7], v[6:7], 0, v[12:13]
	v_lshl_add_u64 v[8:9], v[8:9], 0, v[12:13]
	s_waitcnt vmcnt(60)
	global_store_dword v[10:11], v5, off
	v_fma_f32 v5, v74, v5, v75
	v_lshl_add_u64 v[10:11], v[10:11], 0, v[14:15]
	global_load_dword v52, v[6:7], off
	global_load_dword v53, v[8:9], off
	v_lshl_add_u64 v[6:7], v[6:7], 0, v[12:13]
	v_lshl_add_u64 v[8:9], v[8:9], 0, v[12:13]
	s_waitcnt vmcnt(60)
	global_store_dword v[10:11], v5, off
	v_fma_f32 v5, v76, v5, v77
	v_lshl_add_u64 v[10:11], v[10:11], 0, v[14:15]
	global_load_dword v54, v[6:7], off
	global_load_dword v55, v[8:9], off
	v_lshl_add_u64 v[6:7], v[6:7], 0, v[12:13]
	v_lshl_add_u64 v[8:9], v[8:9], 0, v[12:13]
	s_waitcnt vmcnt(60)
	global_store_dword v[10:11], v5, off
	v_fma_f32 v5, v78, v5, v79
	v_lshl_add_u64 v[10:11], v[10:11], 0, v[14:15]
	global_load_dword v56, v[6:7], off
	global_load_dword v57, v[8:9], off
	v_lshl_add_u64 v[6:7], v[6:7], 0, v[12:13]
	v_lshl_add_u64 v[8:9], v[8:9], 0, v[12:13]
	s_waitcnt vmcnt(60)
	global_store_dword v[10:11], v5, off
	v_fma_f32 v5, v80, v5, v81
	v_lshl_add_u64 v[10:11], v[10:11], 0, v[14:15]
	global_load_dword v58, v[6:7], off
	global_load_dword v59, v[8:9], off
	v_lshl_add_u64 v[6:7], v[6:7], 0, v[12:13]
	v_lshl_add_u64 v[8:9], v[8:9], 0, v[12:13]
	s_waitcnt vmcnt(60)
	global_store_dword v[10:11], v5, off
	v_fma_f32 v5, v82, v5, v83
	v_lshl_add_u64 v[10:11], v[10:11], 0, v[14:15]
	global_load_dword v60, v[6:7], off
	global_load_dword v61, v[8:9], off
	v_lshl_add_u64 v[6:7], v[6:7], 0, v[12:13]
	v_lshl_add_u64 v[8:9], v[8:9], 0, v[12:13]
	s_waitcnt vmcnt(60)
	global_store_dword v[10:11], v5, off
	v_fma_f32 v5, v84, v5, v85
	v_lshl_add_u64 v[10:11], v[10:11], 0, v[14:15]
	global_load_dword v62, v[6:7], off
	global_load_dword v63, v[8:9], off
	v_lshl_add_u64 v[6:7], v[6:7], 0, v[12:13]
	v_lshl_add_u64 v[8:9], v[8:9], 0, v[12:13]
	s_waitcnt vmcnt(60)
	global_store_dword v[10:11], v5, off
	v_fma_f32 v5, v86, v5, v87
	v_lshl_add_u64 v[10:11], v[10:11], 0, v[14:15]
	global_load_dword v64, v[6:7], off
	global_load_dword v65, v[8:9], off
	v_lshl_add_u64 v[6:7], v[6:7], 0, v[12:13]
	v_lshl_add_u64 v[8:9], v[8:9], 0, v[12:13]
	s_waitcnt vmcnt(60)
	global_store_dword v[10:11], v5, off
	v_fma_f32 v5, v88, v5, v89
	v_lshl_add_u64 v[10:11], v[10:11], 0, v[14:15]
	global_load_dword v66, v[6:7], off
	global_load_dword v67, v[8:9], off
	v_lshl_add_u64 v[6:7], v[6:7], 0, v[12:13]
	v_lshl_add_u64 v[8:9], v[8:9], 0, v[12:13]
	s_waitcnt vmcnt(60)
	global_store_dword v[10:11], v5, off
	v_fma_f32 v5, v90, v5, v91
	v_lshl_add_u64 v[10:11], v[10:11], 0, v[14:15]
	global_load_dword v68, v[6:7], off
	global_load_dword v69, v[8:9], off
	v_lshl_add_u64 v[6:7], v[6:7], 0, v[12:13]
	v_lshl_add_u64 v[8:9], v[8:9], 0, v[12:13]
	s_waitcnt vmcnt(60)
	global_store_dword v[10:11], v5, off
	v_fma_f32 v5, v92, v5, v93
	v_lshl_add_u64 v[10:11], v[10:11], 0, v[14:15]
	global_load_dword v70, v[6:7], off
	global_load_dword v71, v[8:9], off
	v_lshl_add_u64 v[6:7], v[6:7], 0, v[12:13]
	v_lshl_add_u64 v[8:9], v[8:9], 0, v[12:13]
	s_waitcnt vmcnt(60)
	global_store_dword v[10:11], v5, off
	v_fma_f32 v5, v94, v5, v95
	v_lshl_add_u64 v[10:11], v[10:11], 0, v[14:15]
	global_load_dword v72, v[6:7], off
	global_load_dword v73, v[8:9], off
	v_lshl_add_u64 v[6:7], v[6:7], 0, v[12:13]
	v_lshl_add_u64 v[8:9], v[8:9], 0, v[12:13]
	s_waitcnt vmcnt(60)
	global_store_dword v[10:11], v5, off
	v_fma_f32 v5, v32, v5, v33
	v_lshl_add_u64 v[10:11], v[10:11], 0, v[14:15]
	global_load_dword v74, v[6:7], off
	global_load_dword v75, v[8:9], off
	v_lshl_add_u64 v[6:7], v[6:7], 0, v[12:13]
	v_lshl_add_u64 v[8:9], v[8:9], 0, v[12:13]
	s_waitcnt vmcnt(60)
	global_store_dword v[10:11], v5, off
	v_fma_f32 v5, v34, v5, v35
	v_lshl_add_u64 v[10:11], v[10:11], 0, v[14:15]
	global_load_dword v76, v[6:7], off
	global_load_dword v77, v[8:9], off
	v_lshl_add_u64 v[6:7], v[6:7], 0, v[12:13]
	v_lshl_add_u64 v[8:9], v[8:9], 0, v[12:13]
	s_waitcnt vmcnt(60)
	global_store_dword v[10:11], v5, off
	v_fma_f32 v5, v36, v5, v37
	v_lshl_add_u64 v[10:11], v[10:11], 0, v[14:15]
	global_load_dword v78, v[6:7], off
	global_load_dword v79, v[8:9], off
	v_lshl_add_u64 v[6:7], v[6:7], 0, v[12:13]
	v_lshl_add_u64 v[8:9], v[8:9], 0, v[12:13]
	s_waitcnt vmcnt(60)
	global_store_dword v[10:11], v5, off
	v_fma_f32 v5, v38, v5, v39
	v_lshl_add_u64 v[10:11], v[10:11], 0, v[14:15]
	global_load_dword v80, v[6:7], off
	global_load_dword v81, v[8:9], off
	v_lshl_add_u64 v[6:7], v[6:7], 0, v[12:13]
	v_lshl_add_u64 v[8:9], v[8:9], 0, v[12:13]
	s_waitcnt vmcnt(60)
	global_store_dword v[10:11], v5, off
	v_fma_f32 v5, v40, v5, v41
	v_lshl_add_u64 v[10:11], v[10:11], 0, v[14:15]
	global_load_dword v82, v[6:7], off
	global_load_dword v83, v[8:9], off
	v_lshl_add_u64 v[6:7], v[6:7], 0, v[12:13]
	v_lshl_add_u64 v[8:9], v[8:9], 0, v[12:13]
	s_waitcnt vmcnt(60)
	global_store_dword v[10:11], v5, off
	v_fma_f32 v5, v42, v5, v43
	v_lshl_add_u64 v[10:11], v[10:11], 0, v[14:15]
	global_load_dword v84, v[6:7], off
	global_load_dword v85, v[8:9], off
	v_lshl_add_u64 v[6:7], v[6:7], 0, v[12:13]
	v_lshl_add_u64 v[8:9], v[8:9], 0, v[12:13]
	s_waitcnt vmcnt(60)
	global_store_dword v[10:11], v5, off
	v_fma_f32 v5, v44, v5, v45
	v_lshl_add_u64 v[10:11], v[10:11], 0, v[14:15]
	global_load_dword v86, v[6:7], off
	global_load_dword v87, v[8:9], off
	v_lshl_add_u64 v[6:7], v[6:7], 0, v[12:13]
	v_lshl_add_u64 v[8:9], v[8:9], 0, v[12:13]
	s_waitcnt vmcnt(60)
	global_store_dword v[10:11], v5, off
	v_fma_f32 v5, v46, v5, v47
	v_lshl_add_u64 v[10:11], v[10:11], 0, v[14:15]
	global_load_dword v88, v[6:7], off
	global_load_dword v89, v[8:9], off
	v_lshl_add_u64 v[6:7], v[6:7], 0, v[12:13]
	v_lshl_add_u64 v[8:9], v[8:9], 0, v[12:13]
	s_waitcnt vmcnt(60)
	global_store_dword v[10:11], v5, off
	v_fma_f32 v5, v48, v5, v49
	v_lshl_add_u64 v[10:11], v[10:11], 0, v[14:15]
	global_load_dword v90, v[6:7], off
	global_load_dword v91, v[8:9], off
	v_lshl_add_u64 v[6:7], v[6:7], 0, v[12:13]
	v_lshl_add_u64 v[8:9], v[8:9], 0, v[12:13]
	s_waitcnt vmcnt(60)
	global_store_dword v[10:11], v5, off
	v_fma_f32 v5, v50, v5, v51
	v_lshl_add_u64 v[10:11], v[10:11], 0, v[14:15]
	global_load_dword v92, v[6:7], off
	global_load_dword v93, v[8:9], off
	v_lshl_add_u64 v[6:7], v[6:7], 0, v[12:13]
	v_lshl_add_u64 v[8:9], v[8:9], 0, v[12:13]
	s_waitcnt vmcnt(60)
	global_store_dword v[10:11], v5, off
	v_fma_f32 v5, v52, v5, v53
	v_lshl_add_u64 v[10:11], v[10:11], 0, v[14:15]
	global_load_dword v94, v[6:7], off
	global_load_dword v95, v[8:9], off
	v_lshl_add_u64 v[6:7], v[6:7], 0, v[12:13]
	v_lshl_add_u64 v[8:9], v[8:9], 0, v[12:13]
	s_waitcnt vmcnt(60)
	global_store_dword v[10:11], v5, off
	v_fma_f32 v5, v54, v5, v55
	v_lshl_add_u64 v[10:11], v[10:11], 0, v[14:15]
	global_load_dword v32, v[6:7], off
	global_load_dword v33, v[8:9], off
	v_lshl_add_u64 v[6:7], v[6:7], 0, v[12:13]
	v_lshl_add_u64 v[8:9], v[8:9], 0, v[12:13]
	s_waitcnt vmcnt(60)
	global_store_dword v[10:11], v5, off
	v_fma_f32 v5, v56, v5, v57
	v_lshl_add_u64 v[10:11], v[10:11], 0, v[14:15]
	global_load_dword v34, v[6:7], off
	global_load_dword v35, v[8:9], off
	v_lshl_add_u64 v[6:7], v[6:7], 0, v[12:13]
	v_lshl_add_u64 v[8:9], v[8:9], 0, v[12:13]
	s_waitcnt vmcnt(60)
	global_store_dword v[10:11], v5, off
	v_fma_f32 v5, v58, v5, v59
	v_lshl_add_u64 v[10:11], v[10:11], 0, v[14:15]
	global_load_dword v36, v[6:7], off
	global_load_dword v37, v[8:9], off
	v_lshl_add_u64 v[6:7], v[6:7], 0, v[12:13]
	v_lshl_add_u64 v[8:9], v[8:9], 0, v[12:13]
	s_waitcnt vmcnt(60)
	global_store_dword v[10:11], v5, off
	v_fma_f32 v5, v60, v5, v61
	v_lshl_add_u64 v[10:11], v[10:11], 0, v[14:15]
	global_load_dword v38, v[6:7], off
	global_load_dword v39, v[8:9], off
	v_lshl_add_u64 v[6:7], v[6:7], 0, v[12:13]
	v_lshl_add_u64 v[8:9], v[8:9], 0, v[12:13]
	s_waitcnt vmcnt(60)
	global_store_dword v[10:11], v5, off
	v_fma_f32 v5, v62, v5, v63
	v_lshl_add_u64 v[10:11], v[10:11], 0, v[14:15]
	global_load_dword v40, v[6:7], off
	global_load_dword v41, v[8:9], off
	v_lshl_add_u64 v[6:7], v[6:7], 0, v[12:13]
	v_lshl_add_u64 v[8:9], v[8:9], 0, v[12:13]
	s_waitcnt vmcnt(60)
	global_store_dword v[10:11], v5, off
	v_fma_f32 v5, v64, v5, v65
	v_lshl_add_u64 v[10:11], v[10:11], 0, v[14:15]
	global_load_dword v42, v[6:7], off
	global_load_dword v43, v[8:9], off
	v_lshl_add_u64 v[6:7], v[6:7], 0, v[12:13]
	v_lshl_add_u64 v[8:9], v[8:9], 0, v[12:13]
	s_waitcnt vmcnt(60)
	global_store_dword v[10:11], v5, off
	v_fma_f32 v5, v66, v5, v67
	v_lshl_add_u64 v[10:11], v[10:11], 0, v[14:15]
	global_load_dword v44, v[6:7], off
	global_load_dword v45, v[8:9], off
	v_lshl_add_u64 v[6:7], v[6:7], 0, v[12:13]
	v_lshl_add_u64 v[8:9], v[8:9], 0, v[12:13]
	s_waitcnt vmcnt(60)
	global_store_dword v[10:11], v5, off
	v_fma_f32 v5, v68, v5, v69
	v_lshl_add_u64 v[10:11], v[10:11], 0, v[14:15]
	global_load_dword v46, v[6:7], off
	global_load_dword v47, v[8:9], off
	v_lshl_add_u64 v[6:7], v[6:7], 0, v[12:13]
	v_lshl_add_u64 v[8:9], v[8:9], 0, v[12:13]
	s_waitcnt vmcnt(60)
	global_store_dword v[10:11], v5, off
	v_fma_f32 v5, v70, v5, v71
	v_lshl_add_u64 v[10:11], v[10:11], 0, v[14:15]
	global_load_dword v48, v[6:7], off
	global_load_dword v49, v[8:9], off
	v_lshl_add_u64 v[6:7], v[6:7], 0, v[12:13]
	v_lshl_add_u64 v[8:9], v[8:9], 0, v[12:13]
	s_waitcnt vmcnt(60)
	global_store_dword v[10:11], v5, off
	v_fma_f32 v5, v72, v5, v73
	v_lshl_add_u64 v[10:11], v[10:11], 0, v[14:15]
	global_load_dword v50, v[6:7], off
	global_load_dword v51, v[8:9], off
	v_lshl_add_u64 v[6:7], v[6:7], 0, v[12:13]
	v_lshl_add_u64 v[8:9], v[8:9], 0, v[12:13]
	s_waitcnt vmcnt(60)
	global_store_dword v[10:11], v5, off
	v_fma_f32 v5, v74, v5, v75
	v_lshl_add_u64 v[10:11], v[10:11], 0, v[14:15]
	global_load_dword v52, v[6:7], off
	global_load_dword v53, v[8:9], off
	v_lshl_add_u64 v[6:7], v[6:7], 0, v[12:13]
	v_lshl_add_u64 v[8:9], v[8:9], 0, v[12:13]
	s_waitcnt vmcnt(60)
	global_store_dword v[10:11], v5, off
	v_fma_f32 v5, v76, v5, v77
	v_lshl_add_u64 v[10:11], v[10:11], 0, v[14:15]
	global_load_dword v54, v[6:7], off
	global_load_dword v55, v[8:9], off
	v_lshl_add_u64 v[6:7], v[6:7], 0, v[12:13]
	v_lshl_add_u64 v[8:9], v[8:9], 0, v[12:13]
	s_waitcnt vmcnt(60)
	global_store_dword v[10:11], v5, off
	v_fma_f32 v5, v78, v5, v79
	v_lshl_add_u64 v[10:11], v[10:11], 0, v[14:15]
	global_load_dword v56, v[6:7], off
	global_load_dword v57, v[8:9], off
	v_lshl_add_u64 v[6:7], v[6:7], 0, v[12:13]
	v_lshl_add_u64 v[8:9], v[8:9], 0, v[12:13]
	s_waitcnt vmcnt(60)
	global_store_dword v[10:11], v5, off
	v_fma_f32 v5, v80, v5, v81
	v_lshl_add_u64 v[10:11], v[10:11], 0, v[14:15]
	global_load_dword v58, v[6:7], off
	global_load_dword v59, v[8:9], off
	v_lshl_add_u64 v[6:7], v[6:7], 0, v[12:13]
	v_lshl_add_u64 v[8:9], v[8:9], 0, v[12:13]
	s_waitcnt vmcnt(60)
	global_store_dword v[10:11], v5, off
	v_fma_f32 v5, v82, v5, v83
	v_lshl_add_u64 v[10:11], v[10:11], 0, v[14:15]
	global_load_dword v60, v[6:7], off
	global_load_dword v61, v[8:9], off
	v_lshl_add_u64 v[6:7], v[6:7], 0, v[12:13]
	v_lshl_add_u64 v[8:9], v[8:9], 0, v[12:13]
	s_waitcnt vmcnt(60)
	global_store_dword v[10:11], v5, off
	v_fma_f32 v5, v84, v5, v85
	v_lshl_add_u64 v[10:11], v[10:11], 0, v[14:15]
	global_load_dword v62, v[6:7], off
	global_load_dword v63, v[8:9], off
	v_lshl_add_u64 v[6:7], v[6:7], 0, v[12:13]
	v_lshl_add_u64 v[8:9], v[8:9], 0, v[12:13]
	s_waitcnt vmcnt(60)
	global_store_dword v[10:11], v5, off
	v_fma_f32 v5, v86, v5, v87
	v_lshl_add_u64 v[10:11], v[10:11], 0, v[14:15]
	global_load_dword v64, v[6:7], off
	global_load_dword v65, v[8:9], off
	v_lshl_add_u64 v[6:7], v[6:7], 0, v[12:13]
	v_lshl_add_u64 v[8:9], v[8:9], 0, v[12:13]
	s_waitcnt vmcnt(60)
	global_store_dword v[10:11], v5, off
	v_fma_f32 v5, v88, v5, v89
	v_lshl_add_u64 v[10:11], v[10:11], 0, v[14:15]
	global_load_dword v66, v[6:7], off
	global_load_dword v67, v[8:9], off
	v_lshl_add_u64 v[6:7], v[6:7], 0, v[12:13]
	v_lshl_add_u64 v[8:9], v[8:9], 0, v[12:13]
	s_waitcnt vmcnt(60)
	global_store_dword v[10:11], v5, off
	v_fma_f32 v5, v90, v5, v91
	v_lshl_add_u64 v[10:11], v[10:11], 0, v[14:15]
	global_load_dword v68, v[6:7], off
	global_load_dword v69, v[8:9], off
	v_lshl_add_u64 v[6:7], v[6:7], 0, v[12:13]
	v_lshl_add_u64 v[8:9], v[8:9], 0, v[12:13]
	s_waitcnt vmcnt(60)
	global_store_dword v[10:11], v5, off
	v_fma_f32 v5, v92, v5, v93
	v_lshl_add_u64 v[10:11], v[10:11], 0, v[14:15]
	global_load_dword v70, v[6:7], off
	global_load_dword v71, v[8:9], off
	v_lshl_add_u64 v[6:7], v[6:7], 0, v[12:13]
	v_lshl_add_u64 v[8:9], v[8:9], 0, v[12:13]
	s_waitcnt vmcnt(60)
	global_store_dword v[10:11], v5, off
	v_fma_f32 v5, v94, v5, v95
	v_lshl_add_u64 v[10:11], v[10:11], 0, v[14:15]
	global_load_dword v72, v[6:7], off
	global_load_dword v73, v[8:9], off
	v_lshl_add_u64 v[6:7], v[6:7], 0, v[12:13]
	v_lshl_add_u64 v[8:9], v[8:9], 0, v[12:13]
	s_waitcnt vmcnt(60)
	global_store_dword v[10:11], v5, off
	v_fma_f32 v5, v32, v5, v33
	v_lshl_add_u64 v[10:11], v[10:11], 0, v[14:15]
	global_load_dword v74, v[6:7], off
	global_load_dword v75, v[8:9], off
	v_lshl_add_u64 v[6:7], v[6:7], 0, v[12:13]
	v_lshl_add_u64 v[8:9], v[8:9], 0, v[12:13]
	s_waitcnt vmcnt(60)
	global_store_dword v[10:11], v5, off
	v_fma_f32 v5, v34, v5, v35
	v_lshl_add_u64 v[10:11], v[10:11], 0, v[14:15]
	global_load_dword v76, v[6:7], off
	global_load_dword v77, v[8:9], off
	v_lshl_add_u64 v[6:7], v[6:7], 0, v[12:13]
	v_lshl_add_u64 v[8:9], v[8:9], 0, v[12:13]
	s_waitcnt vmcnt(60)
	global_store_dword v[10:11], v5, off
	v_fma_f32 v5, v36, v5, v37
	v_lshl_add_u64 v[10:11], v[10:11], 0, v[14:15]
	global_load_dword v78, v[6:7], off
	global_load_dword v79, v[8:9], off
	v_lshl_add_u64 v[6:7], v[6:7], 0, v[12:13]
	v_lshl_add_u64 v[8:9], v[8:9], 0, v[12:13]
	s_waitcnt vmcnt(60)
	global_store_dword v[10:11], v5, off
	v_fma_f32 v5, v38, v5, v39
	v_lshl_add_u64 v[10:11], v[10:11], 0, v[14:15]
	global_load_dword v80, v[6:7], off
	global_load_dword v81, v[8:9], off
	v_lshl_add_u64 v[6:7], v[6:7], 0, v[12:13]
	v_lshl_add_u64 v[8:9], v[8:9], 0, v[12:13]
	s_waitcnt vmcnt(60)
	global_store_dword v[10:11], v5, off
	v_fma_f32 v5, v40, v5, v41
	v_lshl_add_u64 v[10:11], v[10:11], 0, v[14:15]
	global_load_dword v82, v[6:7], off
	global_load_dword v83, v[8:9], off
	v_lshl_add_u64 v[6:7], v[6:7], 0, v[12:13]
	v_lshl_add_u64 v[8:9], v[8:9], 0, v[12:13]
	s_waitcnt vmcnt(60)
	global_store_dword v[10:11], v5, off
	v_fma_f32 v5, v42, v5, v43
	v_lshl_add_u64 v[10:11], v[10:11], 0, v[14:15]
	global_load_dword v84, v[6:7], off
	global_load_dword v85, v[8:9], off
	v_lshl_add_u64 v[6:7], v[6:7], 0, v[12:13]
	v_lshl_add_u64 v[8:9], v[8:9], 0, v[12:13]
	s_waitcnt vmcnt(60)
	global_store_dword v[10:11], v5, off
	v_fma_f32 v5, v44, v5, v45
	v_lshl_add_u64 v[10:11], v[10:11], 0, v[14:15]
	global_load_dword v86, v[6:7], off
	global_load_dword v87, v[8:9], off
	v_lshl_add_u64 v[6:7], v[6:7], 0, v[12:13]
	v_lshl_add_u64 v[8:9], v[8:9], 0, v[12:13]
	s_waitcnt vmcnt(60)
	global_store_dword v[10:11], v5, off
	v_fma_f32 v5, v46, v5, v47
	v_lshl_add_u64 v[10:11], v[10:11], 0, v[14:15]
	global_load_dword v88, v[6:7], off
	global_load_dword v89, v[8:9], off
	v_lshl_add_u64 v[6:7], v[6:7], 0, v[12:13]
	v_lshl_add_u64 v[8:9], v[8:9], 0, v[12:13]
	s_waitcnt vmcnt(60)
	global_store_dword v[10:11], v5, off
	v_fma_f32 v5, v48, v5, v49
	v_lshl_add_u64 v[10:11], v[10:11], 0, v[14:15]
	global_load_dword v90, v[6:7], off
	global_load_dword v91, v[8:9], off
	v_lshl_add_u64 v[6:7], v[6:7], 0, v[12:13]
	v_lshl_add_u64 v[8:9], v[8:9], 0, v[12:13]
	s_waitcnt vmcnt(60)
	global_store_dword v[10:11], v5, off
	v_fma_f32 v5, v50, v5, v51
	v_lshl_add_u64 v[10:11], v[10:11], 0, v[14:15]
	global_load_dword v92, v[6:7], off
	global_load_dword v93, v[8:9], off
	v_lshl_add_u64 v[6:7], v[6:7], 0, v[12:13]
	v_lshl_add_u64 v[8:9], v[8:9], 0, v[12:13]
	s_waitcnt vmcnt(60)
	global_store_dword v[10:11], v5, off
	v_fma_f32 v5, v52, v5, v53
	v_lshl_add_u64 v[10:11], v[10:11], 0, v[14:15]
	global_load_dword v94, v[6:7], off
	global_load_dword v95, v[8:9], off
	v_lshl_add_u64 v[6:7], v[6:7], 0, v[12:13]
	v_lshl_add_u64 v[8:9], v[8:9], 0, v[12:13]
	s_waitcnt vmcnt(60)
	global_store_dword v[10:11], v5, off
	v_fma_f32 v5, v54, v5, v55
	v_lshl_add_u64 v[10:11], v[10:11], 0, v[14:15]
	global_load_dword v32, v[6:7], off
	global_load_dword v33, v[8:9], off
	v_lshl_add_u64 v[6:7], v[6:7], 0, v[12:13]
	v_lshl_add_u64 v[8:9], v[8:9], 0, v[12:13]
	s_waitcnt vmcnt(60)
	global_store_dword v[10:11], v5, off
	v_fma_f32 v5, v56, v5, v57
	v_lshl_add_u64 v[10:11], v[10:11], 0, v[14:15]
	global_load_dword v34, v[6:7], off
	global_load_dword v35, v[8:9], off
	v_lshl_add_u64 v[6:7], v[6:7], 0, v[12:13]
	v_lshl_add_u64 v[8:9], v[8:9], 0, v[12:13]
	s_waitcnt vmcnt(60)
	global_store_dword v[10:11], v5, off
	v_fma_f32 v5, v58, v5, v59
	v_lshl_add_u64 v[10:11], v[10:11], 0, v[14:15]
	global_load_dword v36, v[6:7], off
	global_load_dword v37, v[8:9], off
	v_lshl_add_u64 v[6:7], v[6:7], 0, v[12:13]
	v_lshl_add_u64 v[8:9], v[8:9], 0, v[12:13]
	s_waitcnt vmcnt(60)
	global_store_dword v[10:11], v5, off
	v_fma_f32 v5, v60, v5, v61
	v_lshl_add_u64 v[10:11], v[10:11], 0, v[14:15]
	global_load_dword v38, v[6:7], off
	global_load_dword v39, v[8:9], off
	v_lshl_add_u64 v[6:7], v[6:7], 0, v[12:13]
	v_lshl_add_u64 v[8:9], v[8:9], 0, v[12:13]
	s_waitcnt vmcnt(60)
	global_store_dword v[10:11], v5, off
	v_fma_f32 v5, v62, v5, v63
	v_lshl_add_u64 v[10:11], v[10:11], 0, v[14:15]
	global_load_dword v40, v[6:7], off
	global_load_dword v41, v[8:9], off
	v_lshl_add_u64 v[6:7], v[6:7], 0, v[12:13]
	v_lshl_add_u64 v[8:9], v[8:9], 0, v[12:13]
	s_waitcnt vmcnt(60)
	global_store_dword v[10:11], v5, off
	v_fma_f32 v5, v64, v5, v65
	v_lshl_add_u64 v[10:11], v[10:11], 0, v[14:15]
	global_load_dword v42, v[6:7], off
	global_load_dword v43, v[8:9], off
	v_lshl_add_u64 v[6:7], v[6:7], 0, v[12:13]
	v_lshl_add_u64 v[8:9], v[8:9], 0, v[12:13]
	s_waitcnt vmcnt(60)
	global_store_dword v[10:11], v5, off
	v_fma_f32 v5, v66, v5, v67
	v_lshl_add_u64 v[10:11], v[10:11], 0, v[14:15]
	global_load_dword v44, v[6:7], off
	global_load_dword v45, v[8:9], off
	v_lshl_add_u64 v[6:7], v[6:7], 0, v[12:13]
	v_lshl_add_u64 v[8:9], v[8:9], 0, v[12:13]
	s_waitcnt vmcnt(60)
	global_store_dword v[10:11], v5, off
	v_fma_f32 v5, v68, v5, v69
	v_lshl_add_u64 v[10:11], v[10:11], 0, v[14:15]
	global_load_dword v46, v[6:7], off
	global_load_dword v47, v[8:9], off
	v_lshl_add_u64 v[6:7], v[6:7], 0, v[12:13]
	v_lshl_add_u64 v[8:9], v[8:9], 0, v[12:13]
	s_waitcnt vmcnt(60)
	global_store_dword v[10:11], v5, off
	v_fma_f32 v5, v70, v5, v71
	v_lshl_add_u64 v[10:11], v[10:11], 0, v[14:15]
	global_load_dword v48, v[6:7], off
	global_load_dword v49, v[8:9], off
	v_lshl_add_u64 v[6:7], v[6:7], 0, v[12:13]
	v_lshl_add_u64 v[8:9], v[8:9], 0, v[12:13]
	s_waitcnt vmcnt(60)
	global_store_dword v[10:11], v5, off
	v_fma_f32 v5, v72, v5, v73
	v_lshl_add_u64 v[10:11], v[10:11], 0, v[14:15]
	global_load_dword v50, v[6:7], off
	global_load_dword v51, v[8:9], off
	v_lshl_add_u64 v[6:7], v[6:7], 0, v[12:13]
	v_lshl_add_u64 v[8:9], v[8:9], 0, v[12:13]
	s_waitcnt vmcnt(60)
	global_store_dword v[10:11], v5, off
	v_fma_f32 v5, v74, v5, v75
	v_lshl_add_u64 v[10:11], v[10:11], 0, v[14:15]
	global_load_dword v52, v[6:7], off
	global_load_dword v53, v[8:9], off
	v_lshl_add_u64 v[6:7], v[6:7], 0, v[12:13]
	v_lshl_add_u64 v[8:9], v[8:9], 0, v[12:13]
	s_waitcnt vmcnt(60)
	global_store_dword v[10:11], v5, off
	v_fma_f32 v5, v76, v5, v77
	v_lshl_add_u64 v[10:11], v[10:11], 0, v[14:15]
	global_load_dword v54, v[6:7], off
	global_load_dword v55, v[8:9], off
	v_lshl_add_u64 v[6:7], v[6:7], 0, v[12:13]
	v_lshl_add_u64 v[8:9], v[8:9], 0, v[12:13]
	s_waitcnt vmcnt(60)
	global_store_dword v[10:11], v5, off
	v_fma_f32 v5, v78, v5, v79
	v_lshl_add_u64 v[10:11], v[10:11], 0, v[14:15]
	global_load_dword v56, v[6:7], off
	global_load_dword v57, v[8:9], off
	v_lshl_add_u64 v[6:7], v[6:7], 0, v[12:13]
	v_lshl_add_u64 v[8:9], v[8:9], 0, v[12:13]
	s_waitcnt vmcnt(60)
	global_store_dword v[10:11], v5, off
	v_fma_f32 v5, v80, v5, v81
	v_lshl_add_u64 v[10:11], v[10:11], 0, v[14:15]
	global_load_dword v58, v[6:7], off
	global_load_dword v59, v[8:9], off
	v_lshl_add_u64 v[6:7], v[6:7], 0, v[12:13]
	v_lshl_add_u64 v[8:9], v[8:9], 0, v[12:13]
	s_waitcnt vmcnt(60)
	global_store_dword v[10:11], v5, off
	v_fma_f32 v5, v82, v5, v83
	v_lshl_add_u64 v[10:11], v[10:11], 0, v[14:15]
	global_load_dword v60, v[6:7], off
	global_load_dword v61, v[8:9], off
	v_lshl_add_u64 v[6:7], v[6:7], 0, v[12:13]
	v_lshl_add_u64 v[8:9], v[8:9], 0, v[12:13]
	s_waitcnt vmcnt(60)
	global_store_dword v[10:11], v5, off
	v_fma_f32 v5, v84, v5, v85
	v_lshl_add_u64 v[10:11], v[10:11], 0, v[14:15]
	global_load_dword v62, v[6:7], off
	global_load_dword v63, v[8:9], off
	v_lshl_add_u64 v[6:7], v[6:7], 0, v[12:13]
	v_lshl_add_u64 v[8:9], v[8:9], 0, v[12:13]
	s_waitcnt vmcnt(60)
	global_store_dword v[10:11], v5, off
	v_fma_f32 v5, v86, v5, v87
	v_lshl_add_u64 v[10:11], v[10:11], 0, v[14:15]
	global_load_dword v64, v[6:7], off
	global_load_dword v65, v[8:9], off
	v_lshl_add_u64 v[6:7], v[6:7], 0, v[12:13]
	v_lshl_add_u64 v[8:9], v[8:9], 0, v[12:13]
	s_waitcnt vmcnt(60)
	global_store_dword v[10:11], v5, off
	v_fma_f32 v5, v88, v5, v89
	v_lshl_add_u64 v[10:11], v[10:11], 0, v[14:15]
	global_load_dword v66, v[6:7], off
	global_load_dword v67, v[8:9], off
	v_lshl_add_u64 v[6:7], v[6:7], 0, v[12:13]
	v_lshl_add_u64 v[8:9], v[8:9], 0, v[12:13]
	s_waitcnt vmcnt(60)
	global_store_dword v[10:11], v5, off
	v_fma_f32 v5, v90, v5, v91
	v_lshl_add_u64 v[10:11], v[10:11], 0, v[14:15]
	global_load_dword v68, v[6:7], off
	global_load_dword v69, v[8:9], off
	v_lshl_add_u64 v[6:7], v[6:7], 0, v[12:13]
	v_lshl_add_u64 v[8:9], v[8:9], 0, v[12:13]
	s_waitcnt vmcnt(60)
	global_store_dword v[10:11], v5, off
	v_fma_f32 v5, v92, v5, v93
	v_lshl_add_u64 v[10:11], v[10:11], 0, v[14:15]
	global_load_dword v70, v[6:7], off
	global_load_dword v71, v[8:9], off
	v_lshl_add_u64 v[6:7], v[6:7], 0, v[12:13]
	v_lshl_add_u64 v[8:9], v[8:9], 0, v[12:13]
	s_waitcnt vmcnt(60)
	global_store_dword v[10:11], v5, off
	v_fma_f32 v5, v94, v5, v95
	v_lshl_add_u64 v[10:11], v[10:11], 0, v[14:15]
	global_load_dword v72, v[6:7], off
	global_load_dword v73, v[8:9], off
	v_lshl_add_u64 v[6:7], v[6:7], 0, v[12:13]
	v_lshl_add_u64 v[8:9], v[8:9], 0, v[12:13]
	s_waitcnt vmcnt(60)
	global_store_dword v[10:11], v5, off
	v_fma_f32 v5, v32, v5, v33
	v_lshl_add_u64 v[10:11], v[10:11], 0, v[14:15]
	global_load_dword v74, v[6:7], off
	global_load_dword v75, v[8:9], off
	v_lshl_add_u64 v[6:7], v[6:7], 0, v[12:13]
	v_lshl_add_u64 v[8:9], v[8:9], 0, v[12:13]
	s_waitcnt vmcnt(60)
	global_store_dword v[10:11], v5, off
	v_fma_f32 v5, v34, v5, v35
	v_lshl_add_u64 v[10:11], v[10:11], 0, v[14:15]
	global_load_dword v76, v[6:7], off
	global_load_dword v77, v[8:9], off
	v_lshl_add_u64 v[6:7], v[6:7], 0, v[12:13]
	v_lshl_add_u64 v[8:9], v[8:9], 0, v[12:13]
	s_waitcnt vmcnt(60)
	global_store_dword v[10:11], v5, off
	v_fma_f32 v5, v36, v5, v37
	v_lshl_add_u64 v[10:11], v[10:11], 0, v[14:15]
	global_load_dword v78, v[6:7], off
	global_load_dword v79, v[8:9], off
	v_lshl_add_u64 v[6:7], v[6:7], 0, v[12:13]
	v_lshl_add_u64 v[8:9], v[8:9], 0, v[12:13]
	s_waitcnt vmcnt(60)
	global_store_dword v[10:11], v5, off
	v_fma_f32 v5, v38, v5, v39
	v_lshl_add_u64 v[10:11], v[10:11], 0, v[14:15]
	global_load_dword v80, v[6:7], off
	global_load_dword v81, v[8:9], off
	v_lshl_add_u64 v[6:7], v[6:7], 0, v[12:13]
	v_lshl_add_u64 v[8:9], v[8:9], 0, v[12:13]
	s_waitcnt vmcnt(60)
	global_store_dword v[10:11], v5, off
	v_fma_f32 v5, v40, v5, v41
	v_lshl_add_u64 v[10:11], v[10:11], 0, v[14:15]
	global_load_dword v82, v[6:7], off
	global_load_dword v83, v[8:9], off
	v_lshl_add_u64 v[6:7], v[6:7], 0, v[12:13]
	v_lshl_add_u64 v[8:9], v[8:9], 0, v[12:13]
	s_waitcnt vmcnt(60)
	global_store_dword v[10:11], v5, off
	v_fma_f32 v5, v42, v5, v43
	v_lshl_add_u64 v[10:11], v[10:11], 0, v[14:15]
	global_load_dword v84, v[6:7], off
	global_load_dword v85, v[8:9], off
	v_lshl_add_u64 v[6:7], v[6:7], 0, v[12:13]
	v_lshl_add_u64 v[8:9], v[8:9], 0, v[12:13]
	s_waitcnt vmcnt(60)
	global_store_dword v[10:11], v5, off
	v_fma_f32 v5, v44, v5, v45
	v_lshl_add_u64 v[10:11], v[10:11], 0, v[14:15]
	global_load_dword v86, v[6:7], off
	global_load_dword v87, v[8:9], off
	v_lshl_add_u64 v[6:7], v[6:7], 0, v[12:13]
	v_lshl_add_u64 v[8:9], v[8:9], 0, v[12:13]
	s_waitcnt vmcnt(60)
	global_store_dword v[10:11], v5, off
	v_fma_f32 v5, v46, v5, v47
	v_lshl_add_u64 v[10:11], v[10:11], 0, v[14:15]
	global_load_dword v88, v[6:7], off
	global_load_dword v89, v[8:9], off
	v_lshl_add_u64 v[6:7], v[6:7], 0, v[12:13]
	v_lshl_add_u64 v[8:9], v[8:9], 0, v[12:13]
	s_waitcnt vmcnt(60)
	global_store_dword v[10:11], v5, off
	v_fma_f32 v5, v48, v5, v49
	v_lshl_add_u64 v[10:11], v[10:11], 0, v[14:15]
	global_load_dword v90, v[6:7], off
	global_load_dword v91, v[8:9], off
	v_lshl_add_u64 v[6:7], v[6:7], 0, v[12:13]
	v_lshl_add_u64 v[8:9], v[8:9], 0, v[12:13]
	s_waitcnt vmcnt(60)
	global_store_dword v[10:11], v5, off
	v_fma_f32 v5, v50, v5, v51
	v_lshl_add_u64 v[10:11], v[10:11], 0, v[14:15]
	global_load_dword v92, v[6:7], off
	global_load_dword v93, v[8:9], off
	v_lshl_add_u64 v[6:7], v[6:7], 0, v[12:13]
	v_lshl_add_u64 v[8:9], v[8:9], 0, v[12:13]
	s_waitcnt vmcnt(60)
	global_store_dword v[10:11], v5, off
	v_fma_f32 v5, v52, v5, v53
	v_lshl_add_u64 v[10:11], v[10:11], 0, v[14:15]
	global_load_dword v94, v[6:7], off
	global_load_dword v95, v[8:9], off
	v_lshl_add_u64 v[6:7], v[6:7], 0, v[12:13]
	v_lshl_add_u64 v[8:9], v[8:9], 0, v[12:13]
	s_waitcnt vmcnt(60)
	global_store_dword v[10:11], v5, off
	v_fma_f32 v5, v54, v5, v55
	v_lshl_add_u64 v[10:11], v[10:11], 0, v[14:15]
	global_load_dword v32, v[6:7], off
	global_load_dword v33, v[8:9], off
	v_lshl_add_u64 v[6:7], v[6:7], 0, v[12:13]
	v_lshl_add_u64 v[8:9], v[8:9], 0, v[12:13]
	s_waitcnt vmcnt(60)
	global_store_dword v[10:11], v5, off
	v_fma_f32 v5, v56, v5, v57
	v_lshl_add_u64 v[10:11], v[10:11], 0, v[14:15]
	global_load_dword v34, v[6:7], off
	global_load_dword v35, v[8:9], off
	v_lshl_add_u64 v[6:7], v[6:7], 0, v[12:13]
	v_lshl_add_u64 v[8:9], v[8:9], 0, v[12:13]
	s_waitcnt vmcnt(60)
	global_store_dword v[10:11], v5, off
	v_fma_f32 v5, v58, v5, v59
	v_lshl_add_u64 v[10:11], v[10:11], 0, v[14:15]
	global_load_dword v36, v[6:7], off
	global_load_dword v37, v[8:9], off
	v_lshl_add_u64 v[6:7], v[6:7], 0, v[12:13]
	v_lshl_add_u64 v[8:9], v[8:9], 0, v[12:13]
	s_waitcnt vmcnt(60)
	global_store_dword v[10:11], v5, off
	v_fma_f32 v5, v60, v5, v61
	v_lshl_add_u64 v[10:11], v[10:11], 0, v[14:15]
	global_load_dword v38, v[6:7], off
	global_load_dword v39, v[8:9], off
	v_lshl_add_u64 v[6:7], v[6:7], 0, v[12:13]
	v_lshl_add_u64 v[8:9], v[8:9], 0, v[12:13]
	s_waitcnt vmcnt(60)
	global_store_dword v[10:11], v5, off
	v_fma_f32 v5, v62, v5, v63
	v_lshl_add_u64 v[10:11], v[10:11], 0, v[14:15]
	global_load_dword v40, v[6:7], off
	global_load_dword v41, v[8:9], off
	v_lshl_add_u64 v[6:7], v[6:7], 0, v[12:13]
	v_lshl_add_u64 v[8:9], v[8:9], 0, v[12:13]
	s_waitcnt vmcnt(60)
	global_store_dword v[10:11], v5, off
	v_fma_f32 v5, v64, v5, v65
	v_lshl_add_u64 v[10:11], v[10:11], 0, v[14:15]
	global_load_dword v42, v[6:7], off
	global_load_dword v43, v[8:9], off
	v_lshl_add_u64 v[6:7], v[6:7], 0, v[12:13]
	v_lshl_add_u64 v[8:9], v[8:9], 0, v[12:13]
	s_waitcnt vmcnt(60)
	global_store_dword v[10:11], v5, off
	v_fma_f32 v5, v66, v5, v67
	v_lshl_add_u64 v[10:11], v[10:11], 0, v[14:15]
	global_load_dword v44, v[6:7], off
	global_load_dword v45, v[8:9], off
	v_lshl_add_u64 v[6:7], v[6:7], 0, v[12:13]
	v_lshl_add_u64 v[8:9], v[8:9], 0, v[12:13]
	s_waitcnt vmcnt(60)
	global_store_dword v[10:11], v5, off
	v_fma_f32 v5, v68, v5, v69
	v_lshl_add_u64 v[10:11], v[10:11], 0, v[14:15]
	global_load_dword v46, v[6:7], off
	global_load_dword v47, v[8:9], off
	v_lshl_add_u64 v[6:7], v[6:7], 0, v[12:13]
	v_lshl_add_u64 v[8:9], v[8:9], 0, v[12:13]
	s_waitcnt vmcnt(60)
	global_store_dword v[10:11], v5, off
	v_fma_f32 v5, v70, v5, v71
	v_lshl_add_u64 v[10:11], v[10:11], 0, v[14:15]
	global_load_dword v48, v[6:7], off
	global_load_dword v49, v[8:9], off
	v_lshl_add_u64 v[6:7], v[6:7], 0, v[12:13]
	v_lshl_add_u64 v[8:9], v[8:9], 0, v[12:13]
	s_waitcnt vmcnt(60)
	global_store_dword v[10:11], v5, off
	v_fma_f32 v5, v72, v5, v73
	v_lshl_add_u64 v[10:11], v[10:11], 0, v[14:15]
	global_load_dword v50, v[6:7], off
	global_load_dword v51, v[8:9], off
	v_lshl_add_u64 v[6:7], v[6:7], 0, v[12:13]
	v_lshl_add_u64 v[8:9], v[8:9], 0, v[12:13]
	s_waitcnt vmcnt(60)
	global_store_dword v[10:11], v5, off
	v_fma_f32 v5, v74, v5, v75
	v_lshl_add_u64 v[10:11], v[10:11], 0, v[14:15]
	global_load_dword v52, v[6:7], off
	global_load_dword v53, v[8:9], off
	v_lshl_add_u64 v[6:7], v[6:7], 0, v[12:13]
	v_lshl_add_u64 v[8:9], v[8:9], 0, v[12:13]
	s_waitcnt vmcnt(60)
	global_store_dword v[10:11], v5, off
	v_fma_f32 v5, v76, v5, v77
	v_lshl_add_u64 v[10:11], v[10:11], 0, v[14:15]
	global_load_dword v54, v[6:7], off
	global_load_dword v55, v[8:9], off
	v_lshl_add_u64 v[6:7], v[6:7], 0, v[12:13]
	v_lshl_add_u64 v[8:9], v[8:9], 0, v[12:13]
	s_waitcnt vmcnt(60)
	global_store_dword v[10:11], v5, off
	v_fma_f32 v5, v78, v5, v79
	v_lshl_add_u64 v[10:11], v[10:11], 0, v[14:15]
	global_load_dword v56, v[6:7], off
	global_load_dword v57, v[8:9], off
	v_lshl_add_u64 v[6:7], v[6:7], 0, v[12:13]
	v_lshl_add_u64 v[8:9], v[8:9], 0, v[12:13]
	s_waitcnt vmcnt(60)
	global_store_dword v[10:11], v5, off
	v_fma_f32 v5, v80, v5, v81
	v_lshl_add_u64 v[10:11], v[10:11], 0, v[14:15]
	global_load_dword v58, v[6:7], off
	global_load_dword v59, v[8:9], off
	v_lshl_add_u64 v[6:7], v[6:7], 0, v[12:13]
	v_lshl_add_u64 v[8:9], v[8:9], 0, v[12:13]
	s_waitcnt vmcnt(60)
	global_store_dword v[10:11], v5, off
	v_fma_f32 v5, v82, v5, v83
	v_lshl_add_u64 v[10:11], v[10:11], 0, v[14:15]
	global_load_dword v60, v[6:7], off
	global_load_dword v61, v[8:9], off
	v_lshl_add_u64 v[6:7], v[6:7], 0, v[12:13]
	v_lshl_add_u64 v[8:9], v[8:9], 0, v[12:13]
	s_waitcnt vmcnt(60)
	global_store_dword v[10:11], v5, off
	v_fma_f32 v5, v84, v5, v85
	v_lshl_add_u64 v[10:11], v[10:11], 0, v[14:15]
	global_load_dword v62, v[6:7], off
	global_load_dword v63, v[8:9], off
	v_lshl_add_u64 v[6:7], v[6:7], 0, v[12:13]
	v_lshl_add_u64 v[8:9], v[8:9], 0, v[12:13]
	s_waitcnt vmcnt(60)
	global_store_dword v[10:11], v5, off
	v_fma_f32 v5, v86, v5, v87
	v_lshl_add_u64 v[10:11], v[10:11], 0, v[14:15]
	global_load_dword v64, v[6:7], off
	global_load_dword v65, v[8:9], off
	v_lshl_add_u64 v[6:7], v[6:7], 0, v[12:13]
	v_lshl_add_u64 v[8:9], v[8:9], 0, v[12:13]
	s_waitcnt vmcnt(60)
	global_store_dword v[10:11], v5, off
	v_fma_f32 v5, v88, v5, v89
	v_lshl_add_u64 v[10:11], v[10:11], 0, v[14:15]
	global_load_dword v66, v[6:7], off
	global_load_dword v67, v[8:9], off
	v_lshl_add_u64 v[6:7], v[6:7], 0, v[12:13]
	v_lshl_add_u64 v[8:9], v[8:9], 0, v[12:13]
	s_waitcnt vmcnt(60)
	global_store_dword v[10:11], v5, off
	v_fma_f32 v5, v90, v5, v91
	v_lshl_add_u64 v[10:11], v[10:11], 0, v[14:15]
	global_load_dword v68, v[6:7], off
	global_load_dword v69, v[8:9], off
	v_lshl_add_u64 v[6:7], v[6:7], 0, v[12:13]
	v_lshl_add_u64 v[8:9], v[8:9], 0, v[12:13]
	s_waitcnt vmcnt(60)
	global_store_dword v[10:11], v5, off
	v_fma_f32 v5, v92, v5, v93
	v_lshl_add_u64 v[10:11], v[10:11], 0, v[14:15]
	global_load_dword v70, v[6:7], off
	global_load_dword v71, v[8:9], off
	v_lshl_add_u64 v[6:7], v[6:7], 0, v[12:13]
	v_lshl_add_u64 v[8:9], v[8:9], 0, v[12:13]
	s_waitcnt vmcnt(60)
	global_store_dword v[10:11], v5, off
	v_fma_f32 v5, v94, v5, v95
	v_lshl_add_u64 v[10:11], v[10:11], 0, v[14:15]
	global_load_dword v72, v[6:7], off
	global_load_dword v73, v[8:9], off
	v_lshl_add_u64 v[6:7], v[6:7], 0, v[12:13]
	v_lshl_add_u64 v[8:9], v[8:9], 0, v[12:13]
	s_waitcnt vmcnt(60)
	global_store_dword v[10:11], v5, off
	v_fma_f32 v5, v32, v5, v33
	v_lshl_add_u64 v[10:11], v[10:11], 0, v[14:15]
	global_load_dword v74, v[6:7], off
	global_load_dword v75, v[8:9], off
	v_lshl_add_u64 v[6:7], v[6:7], 0, v[12:13]
	v_lshl_add_u64 v[8:9], v[8:9], 0, v[12:13]
	s_waitcnt vmcnt(60)
	global_store_dword v[10:11], v5, off
	v_fma_f32 v5, v34, v5, v35
	v_lshl_add_u64 v[10:11], v[10:11], 0, v[14:15]
	global_load_dword v76, v[6:7], off
	global_load_dword v77, v[8:9], off
	v_lshl_add_u64 v[6:7], v[6:7], 0, v[12:13]
	v_lshl_add_u64 v[8:9], v[8:9], 0, v[12:13]
	s_waitcnt vmcnt(60)
	global_store_dword v[10:11], v5, off
	v_fma_f32 v5, v36, v5, v37
	v_lshl_add_u64 v[10:11], v[10:11], 0, v[14:15]
	global_load_dword v78, v[6:7], off
	global_load_dword v79, v[8:9], off
	v_lshl_add_u64 v[6:7], v[6:7], 0, v[12:13]
	v_lshl_add_u64 v[8:9], v[8:9], 0, v[12:13]
	s_waitcnt vmcnt(60)
	global_store_dword v[10:11], v5, off
	v_fma_f32 v5, v38, v5, v39
	v_lshl_add_u64 v[10:11], v[10:11], 0, v[14:15]
	global_load_dword v80, v[6:7], off
	global_load_dword v81, v[8:9], off
	v_lshl_add_u64 v[6:7], v[6:7], 0, v[12:13]
	v_lshl_add_u64 v[8:9], v[8:9], 0, v[12:13]
	s_waitcnt vmcnt(60)
	global_store_dword v[10:11], v5, off
	v_fma_f32 v5, v40, v5, v41
	v_lshl_add_u64 v[10:11], v[10:11], 0, v[14:15]
	global_load_dword v82, v[6:7], off
	global_load_dword v83, v[8:9], off
	v_lshl_add_u64 v[6:7], v[6:7], 0, v[12:13]
	v_lshl_add_u64 v[8:9], v[8:9], 0, v[12:13]
	s_waitcnt vmcnt(60)
	global_store_dword v[10:11], v5, off
	v_fma_f32 v5, v42, v5, v43
	v_lshl_add_u64 v[10:11], v[10:11], 0, v[14:15]
	global_load_dword v84, v[6:7], off
	global_load_dword v85, v[8:9], off
	v_lshl_add_u64 v[6:7], v[6:7], 0, v[12:13]
	v_lshl_add_u64 v[8:9], v[8:9], 0, v[12:13]
	s_waitcnt vmcnt(60)
	global_store_dword v[10:11], v5, off
	v_fma_f32 v5, v44, v5, v45
	v_lshl_add_u64 v[10:11], v[10:11], 0, v[14:15]
	global_load_dword v86, v[6:7], off
	global_load_dword v87, v[8:9], off
	v_lshl_add_u64 v[6:7], v[6:7], 0, v[12:13]
	v_lshl_add_u64 v[8:9], v[8:9], 0, v[12:13]
	s_waitcnt vmcnt(60)
	global_store_dword v[10:11], v5, off
	v_fma_f32 v5, v46, v5, v47
	v_lshl_add_u64 v[10:11], v[10:11], 0, v[14:15]
	global_load_dword v88, v[6:7], off
	global_load_dword v89, v[8:9], off
	v_lshl_add_u64 v[6:7], v[6:7], 0, v[12:13]
	v_lshl_add_u64 v[8:9], v[8:9], 0, v[12:13]
	s_waitcnt vmcnt(60)
	global_store_dword v[10:11], v5, off
	v_fma_f32 v5, v48, v5, v49
	v_lshl_add_u64 v[10:11], v[10:11], 0, v[14:15]
	global_load_dword v90, v[6:7], off
	global_load_dword v91, v[8:9], off
	v_lshl_add_u64 v[6:7], v[6:7], 0, v[12:13]
	v_lshl_add_u64 v[8:9], v[8:9], 0, v[12:13]
	s_waitcnt vmcnt(60)
	global_store_dword v[10:11], v5, off
	v_fma_f32 v5, v50, v5, v51
	v_lshl_add_u64 v[10:11], v[10:11], 0, v[14:15]
	global_load_dword v92, v[6:7], off
	global_load_dword v93, v[8:9], off
	v_lshl_add_u64 v[6:7], v[6:7], 0, v[12:13]
	v_lshl_add_u64 v[8:9], v[8:9], 0, v[12:13]
	s_waitcnt vmcnt(60)
	global_store_dword v[10:11], v5, off
	v_fma_f32 v5, v52, v5, v53
	v_lshl_add_u64 v[10:11], v[10:11], 0, v[14:15]
	global_load_dword v94, v[6:7], off
	global_load_dword v95, v[8:9], off
	v_lshl_add_u64 v[6:7], v[6:7], 0, v[12:13]
	v_lshl_add_u64 v[8:9], v[8:9], 0, v[12:13]
	s_waitcnt vmcnt(60)
	global_store_dword v[10:11], v5, off
	v_fma_f32 v5, v54, v5, v55
	v_lshl_add_u64 v[10:11], v[10:11], 0, v[14:15]
	global_load_dword v32, v[6:7], off
	global_load_dword v33, v[8:9], off
	v_lshl_add_u64 v[6:7], v[6:7], 0, v[12:13]
	v_lshl_add_u64 v[8:9], v[8:9], 0, v[12:13]
	s_waitcnt vmcnt(60)
	global_store_dword v[10:11], v5, off
	v_fma_f32 v5, v56, v5, v57
	v_lshl_add_u64 v[10:11], v[10:11], 0, v[14:15]
	global_load_dword v34, v[6:7], off
	global_load_dword v35, v[8:9], off
	v_lshl_add_u64 v[6:7], v[6:7], 0, v[12:13]
	v_lshl_add_u64 v[8:9], v[8:9], 0, v[12:13]
	s_waitcnt vmcnt(60)
	global_store_dword v[10:11], v5, off
	v_fma_f32 v5, v58, v5, v59
	v_lshl_add_u64 v[10:11], v[10:11], 0, v[14:15]
	global_load_dword v36, v[6:7], off
	global_load_dword v37, v[8:9], off
	v_lshl_add_u64 v[6:7], v[6:7], 0, v[12:13]
	v_lshl_add_u64 v[8:9], v[8:9], 0, v[12:13]
	s_waitcnt vmcnt(60)
	global_store_dword v[10:11], v5, off
	v_fma_f32 v5, v60, v5, v61
	v_lshl_add_u64 v[10:11], v[10:11], 0, v[14:15]
	global_load_dword v38, v[6:7], off
	global_load_dword v39, v[8:9], off
	v_lshl_add_u64 v[6:7], v[6:7], 0, v[12:13]
	v_lshl_add_u64 v[8:9], v[8:9], 0, v[12:13]
	s_waitcnt vmcnt(60)
	global_store_dword v[10:11], v5, off
	v_fma_f32 v5, v62, v5, v63
	v_lshl_add_u64 v[10:11], v[10:11], 0, v[14:15]
	global_load_dword v40, v[6:7], off
	global_load_dword v41, v[8:9], off
	v_lshl_add_u64 v[6:7], v[6:7], 0, v[12:13]
	v_lshl_add_u64 v[8:9], v[8:9], 0, v[12:13]
	s_waitcnt vmcnt(60)
	global_store_dword v[10:11], v5, off
	v_fma_f32 v5, v64, v5, v65
	v_lshl_add_u64 v[10:11], v[10:11], 0, v[14:15]
	global_load_dword v42, v[6:7], off
	global_load_dword v43, v[8:9], off
	v_lshl_add_u64 v[6:7], v[6:7], 0, v[12:13]
	v_lshl_add_u64 v[8:9], v[8:9], 0, v[12:13]
	s_waitcnt vmcnt(60)
	global_store_dword v[10:11], v5, off
	v_fma_f32 v5, v66, v5, v67
	v_lshl_add_u64 v[10:11], v[10:11], 0, v[14:15]
	global_load_dword v44, v[6:7], off
	global_load_dword v45, v[8:9], off
	v_lshl_add_u64 v[6:7], v[6:7], 0, v[12:13]
	v_lshl_add_u64 v[8:9], v[8:9], 0, v[12:13]
	s_waitcnt vmcnt(60)
	global_store_dword v[10:11], v5, off
	v_fma_f32 v5, v68, v5, v69
	v_lshl_add_u64 v[10:11], v[10:11], 0, v[14:15]
	global_load_dword v46, v[6:7], off
	global_load_dword v47, v[8:9], off
	v_lshl_add_u64 v[6:7], v[6:7], 0, v[12:13]
	v_lshl_add_u64 v[8:9], v[8:9], 0, v[12:13]
	s_waitcnt vmcnt(60)
	global_store_dword v[10:11], v5, off
	v_fma_f32 v5, v70, v5, v71
	v_lshl_add_u64 v[10:11], v[10:11], 0, v[14:15]
	global_load_dword v48, v[6:7], off
	global_load_dword v49, v[8:9], off
	v_lshl_add_u64 v[6:7], v[6:7], 0, v[12:13]
	v_lshl_add_u64 v[8:9], v[8:9], 0, v[12:13]
	s_waitcnt vmcnt(60)
	global_store_dword v[10:11], v5, off
	v_fma_f32 v5, v72, v5, v73
	v_lshl_add_u64 v[10:11], v[10:11], 0, v[14:15]
	global_load_dword v50, v[6:7], off
	global_load_dword v51, v[8:9], off
	v_lshl_add_u64 v[6:7], v[6:7], 0, v[12:13]
	v_lshl_add_u64 v[8:9], v[8:9], 0, v[12:13]
	s_waitcnt vmcnt(60)
	global_store_dword v[10:11], v5, off
	v_fma_f32 v5, v74, v5, v75
	v_lshl_add_u64 v[10:11], v[10:11], 0, v[14:15]
	global_load_dword v52, v[6:7], off
	global_load_dword v53, v[8:9], off
	v_lshl_add_u64 v[6:7], v[6:7], 0, v[12:13]
	v_lshl_add_u64 v[8:9], v[8:9], 0, v[12:13]
	s_waitcnt vmcnt(60)
	global_store_dword v[10:11], v5, off
	v_fma_f32 v5, v76, v5, v77
	v_lshl_add_u64 v[10:11], v[10:11], 0, v[14:15]
	global_load_dword v54, v[6:7], off
	global_load_dword v55, v[8:9], off
	v_lshl_add_u64 v[6:7], v[6:7], 0, v[12:13]
	v_lshl_add_u64 v[8:9], v[8:9], 0, v[12:13]
	s_waitcnt vmcnt(60)
	global_store_dword v[10:11], v5, off
	v_fma_f32 v5, v78, v5, v79
	v_lshl_add_u64 v[10:11], v[10:11], 0, v[14:15]
	global_load_dword v56, v[6:7], off
	global_load_dword v57, v[8:9], off
	v_lshl_add_u64 v[6:7], v[6:7], 0, v[12:13]
	v_lshl_add_u64 v[8:9], v[8:9], 0, v[12:13]
	s_waitcnt vmcnt(60)
	global_store_dword v[10:11], v5, off
	v_fma_f32 v5, v80, v5, v81
	v_lshl_add_u64 v[10:11], v[10:11], 0, v[14:15]
	global_load_dword v58, v[6:7], off
	global_load_dword v59, v[8:9], off
	v_lshl_add_u64 v[6:7], v[6:7], 0, v[12:13]
	v_lshl_add_u64 v[8:9], v[8:9], 0, v[12:13]
	s_waitcnt vmcnt(60)
	global_store_dword v[10:11], v5, off
	v_fma_f32 v5, v82, v5, v83
	v_lshl_add_u64 v[10:11], v[10:11], 0, v[14:15]
	global_load_dword v60, v[6:7], off
	global_load_dword v61, v[8:9], off
	v_lshl_add_u64 v[6:7], v[6:7], 0, v[12:13]
	v_lshl_add_u64 v[8:9], v[8:9], 0, v[12:13]
	s_waitcnt vmcnt(60)
	global_store_dword v[10:11], v5, off
	v_fma_f32 v5, v84, v5, v85
	v_lshl_add_u64 v[10:11], v[10:11], 0, v[14:15]
	global_load_dword v62, v[6:7], off
	global_load_dword v63, v[8:9], off
	v_lshl_add_u64 v[6:7], v[6:7], 0, v[12:13]
	v_lshl_add_u64 v[8:9], v[8:9], 0, v[12:13]
	s_waitcnt vmcnt(60)
	global_store_dword v[10:11], v5, off
	v_fma_f32 v5, v86, v5, v87
	v_lshl_add_u64 v[10:11], v[10:11], 0, v[14:15]
	global_load_dword v64, v[6:7], off
	global_load_dword v65, v[8:9], off
	v_lshl_add_u64 v[6:7], v[6:7], 0, v[12:13]
	v_lshl_add_u64 v[8:9], v[8:9], 0, v[12:13]
	s_waitcnt vmcnt(60)
	global_store_dword v[10:11], v5, off
	v_fma_f32 v5, v88, v5, v89
	v_lshl_add_u64 v[10:11], v[10:11], 0, v[14:15]
	global_load_dword v66, v[6:7], off
	global_load_dword v67, v[8:9], off
	v_lshl_add_u64 v[6:7], v[6:7], 0, v[12:13]
	v_lshl_add_u64 v[8:9], v[8:9], 0, v[12:13]
	s_waitcnt vmcnt(60)
	global_store_dword v[10:11], v5, off
	v_fma_f32 v5, v90, v5, v91
	v_lshl_add_u64 v[10:11], v[10:11], 0, v[14:15]
	global_load_dword v68, v[6:7], off
	global_load_dword v69, v[8:9], off
	v_lshl_add_u64 v[6:7], v[6:7], 0, v[12:13]
	v_lshl_add_u64 v[8:9], v[8:9], 0, v[12:13]
	s_waitcnt vmcnt(60)
	global_store_dword v[10:11], v5, off
	v_fma_f32 v5, v92, v5, v93
	v_lshl_add_u64 v[10:11], v[10:11], 0, v[14:15]
	global_load_dword v70, v[6:7], off
	global_load_dword v71, v[8:9], off
	v_lshl_add_u64 v[6:7], v[6:7], 0, v[12:13]
	v_lshl_add_u64 v[8:9], v[8:9], 0, v[12:13]
	s_waitcnt vmcnt(60)
	global_store_dword v[10:11], v5, off
	v_fma_f32 v5, v94, v5, v95
	v_lshl_add_u64 v[10:11], v[10:11], 0, v[14:15]
	global_load_dword v72, v[6:7], off
	global_load_dword v73, v[8:9], off
	v_lshl_add_u64 v[6:7], v[6:7], 0, v[12:13]
	v_lshl_add_u64 v[8:9], v[8:9], 0, v[12:13]
	s_waitcnt vmcnt(60)
	global_store_dword v[10:11], v5, off
	v_fma_f32 v5, v32, v5, v33
	v_lshl_add_u64 v[10:11], v[10:11], 0, v[14:15]
	global_load_dword v74, v[6:7], off
	global_load_dword v75, v[8:9], off
	v_lshl_add_u64 v[6:7], v[6:7], 0, v[12:13]
	v_lshl_add_u64 v[8:9], v[8:9], 0, v[12:13]
	s_waitcnt vmcnt(60)
	global_store_dword v[10:11], v5, off
	v_fma_f32 v5, v34, v5, v35
	v_lshl_add_u64 v[10:11], v[10:11], 0, v[14:15]
	global_load_dword v76, v[6:7], off
	global_load_dword v77, v[8:9], off
	v_lshl_add_u64 v[6:7], v[6:7], 0, v[12:13]
	v_lshl_add_u64 v[8:9], v[8:9], 0, v[12:13]
	s_waitcnt vmcnt(60)
	global_store_dword v[10:11], v5, off
	v_fma_f32 v5, v36, v5, v37
	v_lshl_add_u64 v[10:11], v[10:11], 0, v[14:15]
	global_load_dword v78, v[6:7], off
	global_load_dword v79, v[8:9], off
	v_lshl_add_u64 v[6:7], v[6:7], 0, v[12:13]
	v_lshl_add_u64 v[8:9], v[8:9], 0, v[12:13]
	s_waitcnt vmcnt(60)
	global_store_dword v[10:11], v5, off
	v_fma_f32 v5, v38, v5, v39
	v_lshl_add_u64 v[10:11], v[10:11], 0, v[14:15]
	global_load_dword v80, v[6:7], off
	global_load_dword v81, v[8:9], off
	v_lshl_add_u64 v[6:7], v[6:7], 0, v[12:13]
	v_lshl_add_u64 v[8:9], v[8:9], 0, v[12:13]
	s_waitcnt vmcnt(60)
	global_store_dword v[10:11], v5, off
	v_fma_f32 v5, v40, v5, v41
	v_lshl_add_u64 v[10:11], v[10:11], 0, v[14:15]
	global_load_dword v82, v[6:7], off
	global_load_dword v83, v[8:9], off
	v_lshl_add_u64 v[6:7], v[6:7], 0, v[12:13]
	v_lshl_add_u64 v[8:9], v[8:9], 0, v[12:13]
	s_waitcnt vmcnt(60)
	global_store_dword v[10:11], v5, off
	v_fma_f32 v5, v42, v5, v43
	v_lshl_add_u64 v[10:11], v[10:11], 0, v[14:15]
	global_load_dword v84, v[6:7], off
	global_load_dword v85, v[8:9], off
	v_lshl_add_u64 v[6:7], v[6:7], 0, v[12:13]
	v_lshl_add_u64 v[8:9], v[8:9], 0, v[12:13]
	s_waitcnt vmcnt(60)
	global_store_dword v[10:11], v5, off
	v_fma_f32 v5, v44, v5, v45
	v_lshl_add_u64 v[10:11], v[10:11], 0, v[14:15]
	global_load_dword v86, v[6:7], off
	global_load_dword v87, v[8:9], off
	v_lshl_add_u64 v[6:7], v[6:7], 0, v[12:13]
	v_lshl_add_u64 v[8:9], v[8:9], 0, v[12:13]
	s_waitcnt vmcnt(60)
	global_store_dword v[10:11], v5, off
	v_fma_f32 v5, v46, v5, v47
	v_lshl_add_u64 v[10:11], v[10:11], 0, v[14:15]
	global_load_dword v88, v[6:7], off
	global_load_dword v89, v[8:9], off
	v_lshl_add_u64 v[6:7], v[6:7], 0, v[12:13]
	v_lshl_add_u64 v[8:9], v[8:9], 0, v[12:13]
	s_waitcnt vmcnt(60)
	global_store_dword v[10:11], v5, off
	v_fma_f32 v5, v48, v5, v49
	v_lshl_add_u64 v[10:11], v[10:11], 0, v[14:15]
	global_load_dword v90, v[6:7], off
	global_load_dword v91, v[8:9], off
	v_lshl_add_u64 v[6:7], v[6:7], 0, v[12:13]
	v_lshl_add_u64 v[8:9], v[8:9], 0, v[12:13]
	s_waitcnt vmcnt(60)
	global_store_dword v[10:11], v5, off
	v_fma_f32 v5, v50, v5, v51
	v_lshl_add_u64 v[10:11], v[10:11], 0, v[14:15]
	global_load_dword v92, v[6:7], off
	global_load_dword v93, v[8:9], off
	v_lshl_add_u64 v[6:7], v[6:7], 0, v[12:13]
	v_lshl_add_u64 v[8:9], v[8:9], 0, v[12:13]
	s_waitcnt vmcnt(60)
	global_store_dword v[10:11], v5, off
	v_fma_f32 v5, v52, v5, v53
	v_lshl_add_u64 v[10:11], v[10:11], 0, v[14:15]
	global_load_dword v94, v[6:7], off
	global_load_dword v95, v[8:9], off
	v_lshl_add_u64 v[6:7], v[6:7], 0, v[12:13]
	v_lshl_add_u64 v[8:9], v[8:9], 0, v[12:13]
	s_waitcnt vmcnt(60)
	global_store_dword v[10:11], v5, off
	v_fma_f32 v5, v54, v5, v55
	v_lshl_add_u64 v[10:11], v[10:11], 0, v[14:15]
	s_waitcnt vmcnt(58)
	global_store_dword v[10:11], v5, off
	v_fma_f32 v5, v56, v5, v57
	v_lshl_add_u64 v[10:11], v[10:11], 0, v[14:15]
	s_waitcnt vmcnt(56)
	global_store_dword v[10:11], v5, off
	v_fma_f32 v5, v58, v5, v59
	v_lshl_add_u64 v[10:11], v[10:11], 0, v[14:15]
	s_waitcnt vmcnt(54)
	global_store_dword v[10:11], v5, off
	v_fma_f32 v5, v60, v5, v61
	v_lshl_add_u64 v[10:11], v[10:11], 0, v[14:15]
	s_waitcnt vmcnt(52)
	global_store_dword v[10:11], v5, off
	v_fma_f32 v5, v62, v5, v63
	v_lshl_add_u64 v[10:11], v[10:11], 0, v[14:15]
	s_waitcnt vmcnt(50)
	global_store_dword v[10:11], v5, off
	v_fma_f32 v5, v64, v5, v65
	v_lshl_add_u64 v[10:11], v[10:11], 0, v[14:15]
	s_waitcnt vmcnt(48)
	global_store_dword v[10:11], v5, off
	v_fma_f32 v5, v66, v5, v67
	v_lshl_add_u64 v[10:11], v[10:11], 0, v[14:15]
	s_waitcnt vmcnt(46)
	global_store_dword v[10:11], v5, off
	v_fma_f32 v5, v68, v5, v69
	v_lshl_add_u64 v[10:11], v[10:11], 0, v[14:15]
	s_waitcnt vmcnt(44)
	global_store_dword v[10:11], v5, off
	v_fma_f32 v5, v70, v5, v71
	v_lshl_add_u64 v[10:11], v[10:11], 0, v[14:15]
	s_waitcnt vmcnt(42)
	global_store_dword v[10:11], v5, off
	v_fma_f32 v5, v72, v5, v73
	v_lshl_add_u64 v[10:11], v[10:11], 0, v[14:15]
	s_waitcnt vmcnt(40)
	global_store_dword v[10:11], v5, off
	v_fma_f32 v5, v74, v5, v75
	v_lshl_add_u64 v[10:11], v[10:11], 0, v[14:15]
	s_waitcnt vmcnt(38)
	global_store_dword v[10:11], v5, off
	v_fma_f32 v5, v76, v5, v77
	v_lshl_add_u64 v[10:11], v[10:11], 0, v[14:15]
	s_waitcnt vmcnt(36)
	global_store_dword v[10:11], v5, off
	v_fma_f32 v5, v78, v5, v79
	v_lshl_add_u64 v[10:11], v[10:11], 0, v[14:15]
	s_waitcnt vmcnt(34)
	global_store_dword v[10:11], v5, off
	v_fma_f32 v5, v80, v5, v81
	v_lshl_add_u64 v[10:11], v[10:11], 0, v[14:15]
	s_waitcnt vmcnt(32)
	global_store_dword v[10:11], v5, off
	v_fma_f32 v5, v82, v5, v83
	v_lshl_add_u64 v[10:11], v[10:11], 0, v[14:15]
	s_waitcnt vmcnt(30)
	global_store_dword v[10:11], v5, off
	v_fma_f32 v5, v84, v5, v85
	v_lshl_add_u64 v[10:11], v[10:11], 0, v[14:15]
	s_waitcnt vmcnt(28)
	global_store_dword v[10:11], v5, off
	v_fma_f32 v5, v86, v5, v87
	v_lshl_add_u64 v[10:11], v[10:11], 0, v[14:15]
	s_waitcnt vmcnt(26)
	global_store_dword v[10:11], v5, off
	v_fma_f32 v5, v88, v5, v89
	v_lshl_add_u64 v[10:11], v[10:11], 0, v[14:15]
	s_waitcnt vmcnt(24)
	global_store_dword v[10:11], v5, off
	v_fma_f32 v5, v90, v5, v91
	v_lshl_add_u64 v[10:11], v[10:11], 0, v[14:15]
	s_waitcnt vmcnt(22)
	global_store_dword v[10:11], v5, off
	v_fma_f32 v5, v92, v5, v93
	v_lshl_add_u64 v[10:11], v[10:11], 0, v[14:15]
	s_waitcnt vmcnt(20)
	global_store_dword v[10:11], v5, off
	v_fma_f32 v5, v94, v5, v95
	v_lshl_add_u64 v[10:11], v[10:11], 0, v[14:15]
